# G_PLE hand-written epilogue (3-deep residual prefetch) + PP intermediate stored lane-linear (coalesced 1KB bursts) by G_PP, read back by G_PLE
# speedup vs baseline: 1.0081x; 1.0034x over previous
; #define PG8_STAGE(bufoff, gbase, voff) do { _Pragma("unroll") for (int _i = 0; _i < 2; ++_i) \
;         __builtin_amdgcn_global_load_lds((const unsigned*)((const char*)(gbase) + (voff)[_i]), (PG8_LAS unsigned*)(lds + (bufoff) + ldsw + _i * 8192), 16, 0, 0); } while (0)
; #define PG8_WAIT_V(n) asm volatile("s_waitcnt vmcnt(" #n ")" ::: "memory")
; #define PG8_BAR __builtin_amdgcn_s_barrier()
; template <class Epi, class Sched, bool ALIGN_EPI = false, bool SP2 = false, bool I8 = false>
; __device__ __forceinline__ void gemm_phase(PG8_LAS unsigned char* lds, const Gemm g, const Sched& S, const Epi& E) {
;     ...
;     for (int i = 0; i < 2; ++i) { int R, C; stage_rc(tid * 16 + i * 8192, R, C); const int Rb = Epi::PERM ? ((R & ~31) + perm32(R & 31)) : R;
;         voffA[i] = (unsigned)(R * g.lda + C) * 2u; voffB[i] = (unsigned)(Rb * g.ldb + C) * 2u; }
;     const size_t kstep = (size_t)(BK * 2);
;     const size_t hstepA = (size_t)HALF * g.lda * 2, hstepB = (size_t)HALF * g.ldb * 2;
;     const size_t tstepA = 2 * hstepA, tstepB = 2 * hstepB;
;     const unsigned ldsw = (unsigned)wid * 1024u;
;     const int aoff = lds_byte(wr * 64 + fr, fq * 8), boff = lds_byte(wc * 32 + fr, fq * 8);
;     ...
;     const char* cA = (const char*)g.A + (size_t)cur.pm * tstepA + PG8_K0B(cur); const char* cB = (const char*)g.Bt + (size_t)cur.pn * tstepB + PG8_K0B(cur);
;     int nt = PG8_NT(cur);
;     S.a_ready(cur);
;     if constexpr (SP2) {
;         PG8_STAGE(PG8_SB(0, 0), cB, voffB); PG8_STAGE(PG8_SB(0, 1), cB + hstepB, voffB); PG8_STAGE(PG8_SA(0, 0), cA, voffA); PG8_STAGE(PG8_SA(0, 1), cA + hstepA, voffA);
;         if (wr == 1) PG8_BAR;
;         PG8_WAIT_V(2); PG8_BAR;
;         PG8_STAGE(PG8_SB(1, 0), cB + kstep, voffB); PG8_STAGE(PG8_SA(1, 0), cA + kstep, voffA); PG8_STAGE(PG8_SB(1, 1), cB + hstepB + kstep, voffB);
.LBB0_2233:
	v_lshlrev_b32_e32 v1, 4, v0
	s_waitcnt vmcnt(0)
	v_and_b32_e32 v2, 32, v0
	v_bitop3_b32 v1, v1, v2, 48 bitop3:0x6c
	v_lshrrev_b32_e32 v2, 1, v0
	v_lshrrev_b32_e32 v4, 5, v0
	v_and_b32_e32 v2, 24, v2
	v_and_b32_e32 v4, 4, v4
	v_bfe_u32 v5, v0, 2, 2
	s_ashr_i32 s0, s3, 3
	s_waitcnt lgkmcnt(0)
	v_bfe_u32 v3, v0, 2, 4
	v_or3_b32 v2, v4, v5, v2
	v_lshrrev_b32_e32 v4, 3, v0
	s_add_u32 s33, s96, 0x4d500000
	v_and_or_b32 v1, v0, 64, v1
	v_and_or_b32 v5, v4, 48, v3
	v_and_or_b32 v4, v4, 32, v2
	s_addc_u32 s38, s97, 0
	v_lshl_or_b32 v132, v5, 9, v1
	v_bfe_u32 v4, v0, 3, 25
	s_add_u32 s39, s96, 0x3f400000
	v_or_b32_e32 v4, 64, v4
	s_movk_i32 s1, 0x70
	s_addc_u32 s40, s97, 0
	v_and_or_b32 v3, v4, s1, v3
	s_movk_i32 s1, 0x60
	s_add_i32 s0, s2, s0
	v_and_or_b32 v2, v4, s1, v2
	s_ashr_i32 s1, s0, 31
	s_lshr_b32 s1, s1, 25
	s_add_i32 s1, s0, s1
	s_ashr_i32 s2, s1, 7
	s_and_b32 s1, s1, 0xffffff80
	s_sub_i32 s0, s0, s1
	s_bfe_i32 s1, s0, 0x80000
	s_bfe_u32 s1, s1, 0x3000c
	s_add_i32 s1, s0, s1
	s_bfe_i32 s3, s1, 0x80000
	s_and_b32 s1, s1, 0xf8
	s_sub_i32 s0, s0, s1
	s_lshl_b32 s2, s2, 3
	s_sext_i32_i16 s3, s3
	s_sext_i32_i8 s0, s0
	s_lshr_b32 s4, s3, 3
	s_add_i32 s26, s2, s0
	s_lshr_b32 s6, s8, 6
	s_ashr_i32 s27, s26, 31
	s_bfe_i64 s[2:3], s[4:5], 0x100000
	s_lshr_b32 s7, s8, 8
	s_lshl_b32 s41, s6, 10
	s_lshl_b64 s[0:1], s[26:27], 17
	s_lshl_b64 s[2:3], s[2:3], 17
	s_add_u32 s30, s39, s2
	s_addc_u32 s31, s40, s3
	s_add_i32 s27, s41, 0
	s_add_i32 m0, s27, 0x10000
	v_lshl_or_b32 v136, v3, 9, v1
	global_load_lds_dwordx4 v132, s[30:31]
	s_add_i32 m0, s27, 0x12000
	s_add_u32 s2, s30, 0x10000
	global_load_lds_dwordx4 v136, s[30:31]
	s_addc_u32 s3, s31, 0
	s_add_i32 m0, s27, 0x14000
	v_lshl_or_b32 v130, v5, 9, v1
	global_load_lds_dwordx4 v132, s[2:3]
	s_add_i32 m0, s27, 0x16000
	s_add_u32 s28, s33, s0
	s_addc_u32 s29, s38, s1
	s_add_i32 s42, s27, 0x2000
	global_load_lds_dwordx4 v136, s[2:3]
	s_mov_b32 m0, s27
	s_add_u32 s0, s28, 0x10000
	v_lshl_or_b32 v134, v3, 9, v1
	global_load_lds_dwordx4 v130, s[28:29]
	s_mov_b32 m0, s42
	s_addc_u32 s1, s29, 0
	s_add_i32 s43, s27, 0x4000
	global_load_lds_dwordx4 v134, s[28:29]
	s_mov_b32 m0, s43
	s_add_i32 s44, s27, 0x6000
	global_load_lds_dwordx4 v130, s[0:1]
	s_mov_b32 m0, s44
	v_mov_b32_e32 v133, 0
	global_load_lds_dwordx4 v134, s[0:1]
	v_mov_b32_e32 v137, v133
	v_mov_b32_e32 v131, v133
	v_mov_b32_e32 v135, v133
	s_cmp_eq_u32 s7, 1
	v_lshl_add_u64 v[8:9], s[30:31], 0, v[132:133]
	v_lshl_add_u64 v[6:7], s[30:31], 0, v[136:137]
	v_lshl_add_u64 v[2:3], s[28:29], 0, v[130:131]
	s_cselect_b64 s[0:1], -1, 0
	s_cmp_lg_u32 s7, 1
	v_lshl_add_u64 v[4:5], s[28:29], 0, v[134:135]
	s_cbranch_scc1 .LBB0_2235
	s_barrier

; __device__ __forceinline__ u32x4 pack8(const f32x4 v0, const f32x4 v1) { u32x4 w; w.x = cvt_pk_bf16(v0[0], v0[1]); w.y = cvt_pk_bf16(v0[2], v0[3]); w.z = cvt_pk_bf16(v1[0], v1[1]); w.w = cvt_pk_bf16(v1[2], v1[3]); return w; }
; __device__ __forceinline__ void unpack8(const u32x4 w, f32x4& v0, f32x4& v1) { v0 = (f32x4){bf_lo(w.x), bf_hi(w.x), bf_lo(w.y), bf_hi(w.y)}; v1 = (f32x4){bf_lo(w.z), bf_hi(w.z), bf_lo(w.w), bf_hi(w.w)}; }
;     __device__ __forceinline__ void operator()(AccRef acc, const Unit& u, int wr, int wc, int fr, int fq) const {
;     ...
;         for (int s = 0; s < 8; ++s) { const int ai = s >> 2, m = s & 3; const int r = row0 + ai * HALF + m * 16; bf16_t* rowp = O + (size_t)r * ldc + col0;
;                 if (MODE >= 2 && s + 1 < 8) load_row(nxt, row0 + ((s + 1) >> 2) * HALF + ((s + 1) & 3) * 16, col0);
;                 float rs = 1.f; if (MODE == 1) rs = __builtin_amdgcn_rsqf(rstd[r] * (1.0f / 4096.0f) + 1e-6f);
;                 float mx = 0.f;
; #pragma unroll
;                 for (int bj = 0; bj < 2; ++bj) { f32x4 v0 = acc[ai][bj][m][0], v1 = acc[ai][bj][m][1];
;                     if (MODE == 1) { v0 = v0 * rs; v1 = v1 * rs;
; #pragma unroll
;                         for (int j = 0; j < 4; ++j) { const float a = v0[j] > 0.f ? v0[j] : 0.f, b = v1[j] > 0.f ? v1[j] : 0.f; v0[j] = a * a; v1[j] = b * b; } }
;                     if (MODE == 2) { f32x4 g0, g1; unpack8(cur.g[bj], g0, g1); v0 = v0 * g0; v1 = v1 * g1; }
;                     if (MODE == 3) { f32x4 g0, g1, a0, a1; unpack8(cur.g[bj], g0, g1); unpack8(cur.a[bj], a0, a1);
;                         v0 = a0 + v0 * g0; v1 = a1 + v1 * g1;
; #pragma unroll
;                         for (int j = 0; j < 4; ++j) mx = fmaxf(mx, fmaxf(fabsf(v0[j]), fabsf(v1[j]))); }
;                     *(u32x4*)(rowp + bj * HALF) = pack8(v0, v1); }
.LBB0_2246:
	v_mov_b32_e32 v138, v0
	s_nop 0
	v_cvt_pk_bf16_f32 v122, v122, v123
	s_nop 0
	v_cvt_pk_bf16_f32 v123, v124, v125
	s_nop 0
	v_cvt_pk_bf16_f32 v124, v114, v115
	s_nop 0
	v_cvt_pk_bf16_f32 v125, v116, v117
	s_nop 0
	v_lshrrev_b32_e32 v139, 6, v138
	v_and_b32_e32 v138, 63, v138
	v_lshlrev_b32_e32 v138, 4, v138
	v_lshl_add_u32 v138, v139, 14, v138
	s_lshl_b32 s98, s26, 4
	s_add_i32 s98, s98, s51
	s_lshl_b32 s98, s98, 17
	v_add_u32_e32 v138, s98, v138
	v_mov_b32_e32 v139, 0
	v_lshl_add_u64 v[138:139], s[2:3], 0, v[138:139]
	global_store_dwordx4 v[138:139], v[122:125], off
	s_nop 0
	v_cvt_pk_bf16_f32 v114, v126, v127
	s_nop 0
	v_cvt_pk_bf16_f32 v115, v128, v129
	s_nop 0
	v_cvt_pk_bf16_f32 v116, v118, v119
	s_nop 0
	v_cvt_pk_bf16_f32 v117, v120, v121
	global_store_dwordx4 v[138:139], v[114:117], off offset:1024
	s_nop 0
	v_cvt_pk_bf16_f32 v106, v106, v107
	s_nop 0
	v_cvt_pk_bf16_f32 v107, v108, v109
	s_nop 0
	v_cvt_pk_bf16_f32 v108, v98, v99
	s_nop 0
	v_cvt_pk_bf16_f32 v109, v100, v101
	s_nop 1
	s_mov_b64 s[98:99], 0x800
	v_lshl_add_u64 v[114:115], v[138:139], 0, s[98:99]
	global_store_dwordx4 v[114:115], v[106:109], off
	s_nop 0
	v_cvt_pk_bf16_f32 v98, v110, v111
	s_nop 0
	v_cvt_pk_bf16_f32 v99, v112, v113
	s_nop 0
	v_cvt_pk_bf16_f32 v100, v102, v103
	s_nop 0
	v_cvt_pk_bf16_f32 v101, v104, v105
	global_store_dwordx4 v[114:115], v[98:101], off offset:1024
	s_nop 0
	v_cvt_pk_bf16_f32 v90, v90, v91
	s_nop 0
	v_cvt_pk_bf16_f32 v91, v92, v93
	s_nop 0
	v_cvt_pk_bf16_f32 v92, v82, v83
	s_nop 0
	v_cvt_pk_bf16_f32 v93, v84, v85
	s_nop 1
	s_mov_b64 s[98:99], 0x1000
	v_lshl_add_u64 v[98:99], v[138:139], 0, s[98:99]
	global_store_dwordx4 v[98:99], v[90:93], off
	s_nop 0
	v_cvt_pk_bf16_f32 v82, v94, v95
	s_nop 0
	v_cvt_pk_bf16_f32 v83, v96, v97
	s_nop 0
	v_cvt_pk_bf16_f32 v84, v86, v87
	s_nop 0
	v_cvt_pk_bf16_f32 v85, v88, v89
	global_store_dwordx4 v[98:99], v[82:85], off offset:1024
	s_nop 0
	v_cvt_pk_bf16_f32 v58, v58, v59
	s_nop 0
	v_cvt_pk_bf16_f32 v59, v60, v61
	s_nop 0
	v_cvt_pk_bf16_f32 v60, v50, v51
	s_nop 0
	v_cvt_pk_bf16_f32 v61, v52, v53
	s_nop 1
	s_mov_b64 s[98:99], 0x1800
	v_lshl_add_u64 v[82:83], v[138:139], 0, s[98:99]
	global_store_dwordx4 v[82:83], v[58:61], off
	s_nop 0
	v_cvt_pk_bf16_f32 v50, v62, v63
	s_nop 0
	v_cvt_pk_bf16_f32 v51, v64, v65
	s_nop 0
	v_cvt_pk_bf16_f32 v52, v54, v55
	s_nop 0
	v_cvt_pk_bf16_f32 v53, v56, v57
	s_mov_b64 s[98:99], 0x2000
	global_store_dwordx4 v[82:83], v[50:53], off offset:1024
	s_nop 0
	v_lshl_add_u64 v[56:57], v[138:139], 0, s[98:99]
	s_nop 0
	v_cvt_pk_bf16_f32 v50, v78, v79
	v_lshl_add_u64 v[54:55], v[138:139], 0, s[98:99]
	s_nop 0
	v_cvt_pk_bf16_f32 v51, v80, v81
	s_nop 0
	v_cvt_pk_bf16_f32 v52, v70, v71
	s_nop 0
	v_cvt_pk_bf16_f32 v53, v72, v73
	global_store_dwordx4 v[56:57], v[50:53], off
	s_andn2_b64 vcc, exec, s[4:5]
	s_mov_b64 s[4:5], -1
	s_nop 0
	v_cvt_pk_bf16_f32 v50, v74, v75
	s_nop 0
	v_cvt_pk_bf16_f32 v51, v76, v77
	s_nop 0
	v_cvt_pk_bf16_f32 v52, v66, v67
	s_nop 0
	v_cvt_pk_bf16_f32 v53, v68, v69
	global_store_dwordx4 v[54:55], v[50:53], off offset:1024
	s_nop 0
	v_cvt_pk_bf16_f32 v42, v42, v43
	s_nop 0
	v_cvt_pk_bf16_f32 v43, v44, v45
	s_nop 0
	v_cvt_pk_bf16_f32 v44, v34, v35
	s_nop 0
	v_cvt_pk_bf16_f32 v45, v36, v37
	s_nop 1
	s_mov_b64 s[98:99], 0x2800
	v_lshl_add_u64 v[50:51], v[138:139], 0, s[98:99]
	global_store_dwordx4 v[50:51], v[42:45], off
	s_nop 0
	v_cvt_pk_bf16_f32 v34, v46, v47
	s_nop 0
	v_cvt_pk_bf16_f32 v35, v48, v49
	s_nop 0
	v_cvt_pk_bf16_f32 v36, v38, v39
	s_nop 0
	v_cvt_pk_bf16_f32 v37, v40, v41
	global_store_dwordx4 v[50:51], v[34:37], off offset:1024
	s_nop 0
	v_cvt_pk_bf16_f32 v26, v26, v27
	s_nop 0
	v_cvt_pk_bf16_f32 v27, v28, v29
	s_nop 0
	v_cvt_pk_bf16_f32 v28, v18, v19
	s_nop 0
	v_cvt_pk_bf16_f32 v29, v20, v21
	s_nop 1
	s_mov_b64 s[98:99], 0x3000
	v_lshl_add_u64 v[34:35], v[138:139], 0, s[98:99]
	global_store_dwordx4 v[34:35], v[26:29], off
	s_nop 0
	v_cvt_pk_bf16_f32 v18, v30, v31
	s_nop 0
	v_cvt_pk_bf16_f32 v19, v32, v33
	s_nop 0
	v_cvt_pk_bf16_f32 v20, v22, v23
	s_nop 0
	v_cvt_pk_bf16_f32 v21, v24, v25
	global_store_dwordx4 v[34:35], v[18:21], off offset:1024
	s_nop 0
	v_cvt_pk_bf16_f32 v10, v10, v11
	s_nop 0
	v_cvt_pk_bf16_f32 v11, v12, v13
	s_nop 0
	v_cvt_pk_bf16_f32 v12, v2, v3
	s_nop 0
	v_cvt_pk_bf16_f32 v13, v4, v5
	s_nop 1
	s_mov_b64 s[98:99], 0x3800
	v_lshl_add_u64 v[18:19], v[138:139], 0, s[98:99]
	global_store_dwordx4 v[18:19], v[10:13], off
	s_nop 0
	v_cvt_pk_bf16_f32 v2, v14, v15
	s_nop 0
	v_cvt_pk_bf16_f32 v3, v16, v17
	s_nop 0
	v_cvt_pk_bf16_f32 v4, v6, v7
	s_nop 0
	v_cvt_pk_bf16_f32 v5, v8, v9
	global_store_dwordx4 v[18:19], v[2:5], off offset:1024
	s_cbranch_vccnz .LBB0_2237
	s_andn2_b64 vcc, exec, s[0:1]
	s_cbranch_vccnz .LBB0_2236
	s_barrier
	s_branch .LBB0_2236

;     __device__ __forceinline__ void load_row(RowIn& R, size_t off) const {
; #pragma unroll
;         for (int bj = 0; bj < 2; ++bj)
; #pragma unroll
;             for (int n = 0; n < 2; ++n) { const size_t o = off + bj * HALF + n * 16; R.b[bj][n] = *(const f32x4*)(res + o); if (MODE == 1) R.pw[bj][n] = *(const u32x2*)(PP + o); }
;     }
;     __device__ __forceinline__ void operator()(const typename AccT<I8>::type (&acc)[2][2][4][2], const Unit& u, int wr, int wc, int fr, int fq) const {
;         const int row0 = u.pm * BM + wr * 64 + fr, col0 = u.pn * BM + wc * 32 + 4 * fq;
;         f32x4 sv[2][2];
;         if (I8) {
; #pragma unroll
;             for (int bj = 0; bj < 2; ++bj)
; #pragma unroll
;                 for (int n = 0; n < 2; ++n) sv[bj][n] = *(const f32x4*)(swc + col0 + bj * HALF + n * 16);
;         }
;         float rsv[8];
; #pragma unroll
;         for (int s = 0; s < 8; ++s) { const int r = row0 + (s >> 2) * HALF + (s & 3) * 16; float rs = 1.f; if (MODE == 1) rs = __builtin_amdgcn_rsqf(rstd[r] * (1.0f / 4096.0f) + 1e-6f); if (I8) rs *= sxr[r]; rsv[s] = rs; }
;         RowIn cur, nxt;
;         load_row(cur, (size_t)row0 * 4096 + col0);
; #pragma unroll
;         for (int s = 0; s < 8; ++s) { const int ai = s >> 2, m = s & 3; const int r = row0 + ai * HALF + m * 16; const size_t off = (size_t)r * 4096 + col0;
;                 if (s + 1 < 8) load_row(nxt, (size_t)(row0 + ((s + 1) >> 2) * HALF + ((s + 1) & 3) * 16) * 4096 + col0);
.LBB0_2325:
	s_lshl_b32 s49, s2, 4
	s_add_i32 s49, s49, s48
	s_lshl_b32 s49, s49, 17
	v_readlane_b32 s54, v254, 14
	v_readlane_b32 s55, v254, 15
	v_lshrrev_b32_e32 v194, 2, v0
	v_and_b32_e32 v194, 64, v194
	v_and_b32_e32 v195, 15, v0
	v_lshl_add_u32 v194, s2, 8, v194
	v_add_u32_e32 v194, v194, v195
	s_lshl_b32 s2, s48, 8
	v_lshrrev_b32_e32 v195, 1, v0
	v_and_b32_e32 v195, 0x60, v195
	v_lshrrev_b32_e32 v255, 2, v0
	v_and_b32_e32 v255, 12, v255
	v_or3_b32 v195, v195, s2, v255
	v_lshlrev_b32_e32 v190, 14, v194
	v_lshl_add_u32 v190, v195, 2, v190
	v_and_b32_e32 v191, 63, v0
	v_lshlrev_b32_e32 v191, 4, v191
	v_lshrrev_b32_e32 v255, 6, v0
	v_lshl_add_u32 v191, v255, 14, v191
	v_add_u32_e32 v191, s49, v191
	v_lshlrev_b32_e32 v194, 2, v194
	v_lshlrev_b32_e32 v195, 2, v195
	global_load_dword v242, v194, s[6:7] offset:0
	global_load_dword v243, v194, s[6:7] offset:64
	global_load_dword v244, v194, s[6:7] offset:128
	global_load_dword v245, v194, s[6:7] offset:192
	global_load_dword v246, v194, s[6:7] offset:512
	global_load_dword v247, v194, s[6:7] offset:576
	global_load_dword v248, v194, s[6:7] offset:640
	global_load_dword v249, v194, s[6:7] offset:704
	global_load_dword v250, v194, s[10:11] offset:0
	global_load_dword v251, v194, s[10:11] offset:64
	global_load_dword v252, v194, s[10:11] offset:128
	global_load_dword v253, v194, s[10:11] offset:192
	global_load_dword v182, v194, s[10:11] offset:512
	global_load_dword v188, v194, s[10:11] offset:576
	global_load_dword v192, v194, s[10:11] offset:640
	global_load_dword v196, v194, s[10:11] offset:704
	global_load_dwordx4 v[58:61], v195, s[12:13] offset:0
	global_load_dwordx4 v[66:69], v195, s[12:13] offset:64
	global_load_dwordx4 v[74:77], v195, s[12:13] offset:512
	global_load_dwordx4 v[78:81], v195, s[12:13] offset:576
	global_load_dwordx4 v[146:149], v190, s[54:55] offset:0
	global_load_dwordx4 v[150:153], v190, s[54:55] offset:64
	global_load_dwordx4 v[154:157], v190, s[54:55] offset:512
	global_load_dwordx4 v[158:161], v190, s[54:55] offset:576
	global_load_dwordx4 v[162:165], v191, s[8:9] offset:0
	global_load_dwordx4 v[178:181], v191, s[8:9] offset:1024
	v_add_u32_e32 v194, 0x40000, v190
	v_add_u32_e32 v195, 0x800, v191
	global_load_dwordx4 v[198:201], v194, s[54:55] offset:0
	global_load_dwordx4 v[202:205], v194, s[54:55] offset:64
	global_load_dwordx4 v[206:209], v194, s[54:55] offset:512
	global_load_dwordx4 v[210:213], v194, s[54:55] offset:576
	global_load_dwordx4 v[184:187], v195, s[8:9] offset:0
	global_load_dwordx4 v[214:217], v195, s[8:9] offset:1024
	v_add_u32_e32 v194, 0x80000, v190
	v_add_u32_e32 v195, 0x1000, v191
	global_load_dwordx4 v[218:221], v194, s[54:55] offset:0
	global_load_dwordx4 v[222:225], v194, s[54:55] offset:64
	global_load_dwordx4 v[226:229], v194, s[54:55] offset:512
	global_load_dwordx4 v[230:233], v194, s[54:55] offset:576
	global_load_dwordx4 v[234:237], v195, s[8:9] offset:0
	global_load_dwordx4 v[238:241], v195, s[8:9] offset:1024
	v_mov_b32_e32 v255, 0xbfb8aa3b
	v_cvt_f32_i32_e32 v142, v142
	v_cvt_f32_i32_e32 v143, v143
	v_cvt_f32_i32_e32 v144, v144
	v_cvt_f32_i32_e32 v145, v145
	v_cvt_f32_i32_e32 v138, v138
	v_cvt_f32_i32_e32 v139, v139
	v_cvt_f32_i32_e32 v140, v140
	v_cvt_f32_i32_e32 v141, v141
	v_cvt_f32_i32_e32 v134, v134
	v_cvt_f32_i32_e32 v135, v135
	v_cvt_f32_i32_e32 v136, v136
	v_cvt_f32_i32_e32 v137, v137
	v_cvt_f32_i32_e32 v130, v130
	v_cvt_f32_i32_e32 v131, v131
	v_cvt_f32_i32_e32 v132, v132
	v_cvt_f32_i32_e32 v133, v133
	v_cvt_f32_i32_e32 v126, v126
	v_cvt_f32_i32_e32 v127, v127
	v_cvt_f32_i32_e32 v128, v128
	v_cvt_f32_i32_e32 v129, v129
	v_cvt_f32_i32_e32 v122, v122
	v_cvt_f32_i32_e32 v123, v123
	v_cvt_f32_i32_e32 v124, v124
	v_cvt_f32_i32_e32 v125, v125
	v_cvt_f32_i32_e32 v118, v118
	v_cvt_f32_i32_e32 v119, v119
	v_cvt_f32_i32_e32 v120, v120
	v_cvt_f32_i32_e32 v121, v121
	v_cvt_f32_i32_e32 v114, v114
	v_cvt_f32_i32_e32 v115, v115
	v_cvt_f32_i32_e32 v116, v116
	v_cvt_f32_i32_e32 v117, v117
	v_cvt_f32_i32_e32 v110, v110
	v_cvt_f32_i32_e32 v111, v111
	v_cvt_f32_i32_e32 v112, v112
	v_cvt_f32_i32_e32 v113, v113
	v_cvt_f32_i32_e32 v106, v106
	v_cvt_f32_i32_e32 v107, v107
	v_cvt_f32_i32_e32 v108, v108
	v_cvt_f32_i32_e32 v109, v109
	v_cvt_f32_i32_e32 v102, v102
	v_cvt_f32_i32_e32 v103, v103
	v_cvt_f32_i32_e32 v104, v104
	v_cvt_f32_i32_e32 v105, v105
	v_cvt_f32_i32_e32 v98, v98
	v_cvt_f32_i32_e32 v99, v99
	v_cvt_f32_i32_e32 v100, v100
	v_cvt_f32_i32_e32 v101, v101
	v_cvt_f32_i32_e32 v94, v94
	v_cvt_f32_i32_e32 v95, v95
	v_cvt_f32_i32_e32 v96, v96
	v_cvt_f32_i32_e32 v97, v97
	v_cvt_f32_i32_e32 v90, v90
	v_cvt_f32_i32_e32 v91, v91
	v_cvt_f32_i32_e32 v92, v92
	v_cvt_f32_i32_e32 v93, v93
	v_cvt_f32_i32_e32 v86, v86
	v_cvt_f32_i32_e32 v87, v87
	v_cvt_f32_i32_e32 v88, v88
	v_cvt_f32_i32_e32 v89, v89
	v_cvt_f32_i32_e32 v82, v82
	v_cvt_f32_i32_e32 v83, v83
	v_cvt_f32_i32_e32 v84, v84
	v_cvt_f32_i32_e32 v85, v85
	v_cvt_f32_i32_e32 v70, v70
	v_cvt_f32_i32_e32 v71, v71
	v_cvt_f32_i32_e32 v72, v72
	v_cvt_f32_i32_e32 v73, v73
	v_cvt_f32_i32_e32 v62, v62
	v_cvt_f32_i32_e32 v63, v63
	v_cvt_f32_i32_e32 v64, v64
	v_cvt_f32_i32_e32 v65, v65
	v_cvt_f32_i32_e32 v54, v54
	v_cvt_f32_i32_e32 v55, v55
	v_cvt_f32_i32_e32 v56, v56
	v_cvt_f32_i32_e32 v57, v57
	v_cvt_f32_i32_e32 v50, v50
	v_cvt_f32_i32_e32 v51, v51
	v_cvt_f32_i32_e32 v52, v52
	v_cvt_f32_i32_e32 v53, v53
	v_cvt_f32_i32_e32 v46, v46
	v_cvt_f32_i32_e32 v47, v47
	v_cvt_f32_i32_e32 v48, v48
	v_cvt_f32_i32_e32 v49, v49
	v_cvt_f32_i32_e32 v42, v42
	v_cvt_f32_i32_e32 v43, v43
	v_cvt_f32_i32_e32 v44, v44
	v_cvt_f32_i32_e32 v45, v45
	v_cvt_f32_i32_e32 v38, v38
	v_cvt_f32_i32_e32 v39, v39
	v_cvt_f32_i32_e32 v40, v40
	v_cvt_f32_i32_e32 v41, v41
	v_cvt_f32_i32_e32 v34, v34
	v_cvt_f32_i32_e32 v35, v35
	v_cvt_f32_i32_e32 v36, v36
	v_cvt_f32_i32_e32 v37, v37
	v_cvt_f32_i32_e32 v30, v30
	v_cvt_f32_i32_e32 v31, v31
	v_cvt_f32_i32_e32 v32, v32
	v_cvt_f32_i32_e32 v33, v33
	v_cvt_f32_i32_e32 v26, v26
	v_cvt_f32_i32_e32 v27, v27
	v_cvt_f32_i32_e32 v28, v28
	v_cvt_f32_i32_e32 v29, v29
	v_cvt_f32_i32_e32 v22, v22
	v_cvt_f32_i32_e32 v23, v23
	v_cvt_f32_i32_e32 v24, v24
	v_cvt_f32_i32_e32 v25, v25
	v_cvt_f32_i32_e32 v18, v18
	v_cvt_f32_i32_e32 v19, v19
	v_cvt_f32_i32_e32 v20, v20
	v_cvt_f32_i32_e32 v21, v21
	v_cvt_f32_i32_e32 v14, v14
	v_cvt_f32_i32_e32 v15, v15
	v_cvt_f32_i32_e32 v16, v16
	v_cvt_f32_i32_e32 v17, v17
	v_cvt_f32_i32_e32 v10, v10
	v_cvt_f32_i32_e32 v11, v11
	v_cvt_f32_i32_e32 v12, v12
	v_cvt_f32_i32_e32 v13, v13
	v_cvt_f32_i32_e32 v6, v6
	v_cvt_f32_i32_e32 v7, v7
	v_cvt_f32_i32_e32 v8, v8
	v_cvt_f32_i32_e32 v9, v9
	v_cvt_f32_i32_e32 v2, v2
	v_cvt_f32_i32_e32 v3, v3
	v_cvt_f32_i32_e32 v4, v4
	v_cvt_f32_i32_e32 v5, v5
	s_waitcnt vmcnt(22)
; __device__ __forceinline__ unsigned cvt_pk_bf16(float lo, float hi) { unsigned r; asm volatile("s_nop 0\n\tv_cvt_pk_bf16_f32 %0, %1, %2" : "=v"(r) : "v"(lo), "v"(hi)); return r; }
;     __device__ __forceinline__ void operator()(const typename AccT<I8>::type (&acc)[2][2][4][2], const Unit& u, int wr, int wc, int fr, int fq) const {
;     ...
;         for (int s = 0; s < 8; ++s) { const int r = row0 + (s >> 2) * HALF + (s & 3) * 16; float rs = 1.f; if (MODE == 1) rs = __builtin_amdgcn_rsqf(rstd[r] * (1.0f / 4096.0f) + 1e-6f); if (I8) rs *= sxr[r]; rsv[s] = rs; }
;         RowIn cur, nxt;
;         load_row(cur, (size_t)row0 * 4096 + col0);
; #pragma unroll
;         for (int s = 0; s < 8; ++s) { const int ai = s >> 2, m = s & 3; const int r = row0 + ai * HALF + m * 16; const size_t off = (size_t)r * 4096 + col0;
;                 if (s + 1 < 8) load_row(nxt, (size_t)(row0 + ((s + 1) >> 2) * HALF + ((s + 1) & 3) * 16) * 4096 + col0);
;                 const float rs = rsv[s];
;                 float ss = 0.f, mx = 0.f;
; #pragma unroll
;                 for (int bj = 0; bj < 2; ++bj)
; #pragma unroll
;                     for (int n = 0; n < 2; ++n) { const size_t o = off + bj * HALF + n * 16; const f32x4 b = cur.b[bj][n]; f32x4 v;
;                         if constexpr (I8) v = __builtin_convertvector(acc[ai][bj][m][n], f32x4) * rs * sv[bj][n]; else v = acc[ai][bj][m][n];
;                         if (MODE == 1) { const u32x2 pw = cur.pw[bj][n]; const f32x4 pp = (f32x4){bf_lo(pw.x), bf_hi(pw.x), bf_lo(pw.y), bf_hi(pw.y)}; v = sig4(I8 ? v : v * rs) * pp; }
;                         const f32x4 x = b + v; *(f32x4*)(out + o) = x;
;                         if (MODE == 0 && XB) { u32x2 w; w.x = cvt_pk_bf16(x[0], x[1]); w.y = cvt_pk_bf16(x[2], x[3]); *(u32x2*)(XB + o) = w; ss += (x[0] * x[0] + x[1] * x[1]) + (x[2] * x[2] + x[3] * x[3]);
;                             if (RM) mx = fmaxf(fmaxf(mx, fmaxf(fabsf(x[0]), fabsf(x[1]))), fmaxf(fabsf(x[2]), fabsf(x[3]))); } }
;                 if (MODE == 0 && XB) { ss += __shfl_xor(ss, 16); ss += __shfl_xor(ss, 32); if (fq == 0) unsafeAtomicAdd(SS + r, ss);
;                     if (RM) { mx = fmaxf(mx, __shfl_xor(mx, 16)); mx = fmaxf(mx, __shfl_xor(mx, 32)); if (fq == 0) atomicMax(RM + r, __builtin_bit_cast(unsigned, mx)); } }
;                 cur = nxt; }
	v_fmamk_f32 v242, v242, 0x39800000, v197
	v_fmamk_f32 v243, v243, 0x39800000, v197
	v_fmamk_f32 v244, v244, 0x39800000, v197
	v_fmamk_f32 v245, v245, 0x39800000, v197
	v_fmamk_f32 v246, v246, 0x39800000, v197
	v_fmamk_f32 v247, v247, 0x39800000, v197
	v_fmamk_f32 v248, v248, 0x39800000, v197
	v_fmamk_f32 v249, v249, 0x39800000, v197
	v_rsq_f32_e32 v242, v242
	v_rsq_f32_e32 v243, v243
	v_rsq_f32_e32 v244, v244
	v_rsq_f32_e32 v245, v245
	v_rsq_f32_e32 v246, v246
	v_rsq_f32_e32 v247, v247
	v_rsq_f32_e32 v248, v248
	v_rsq_f32_e32 v249, v249
	v_mul_f32_e32 v242, v250, v242
	v_mul_f32_e32 v243, v251, v243
	v_mul_f32_e32 v244, v252, v244
	v_mul_f32_e32 v245, v253, v245
	v_mul_f32_e32 v246, v182, v246
	v_mul_f32_e32 v247, v188, v247
	v_mul_f32_e32 v248, v192, v248
	v_mul_f32_e32 v249, v196, v249
	s_waitcnt vmcnt(18)
	v_pk_mul_f32 v[142:143], v[242:243], v[142:143] op_sel:[0,0] op_sel_hi:[0,1]
	v_pk_mul_f32 v[144:145], v[242:243], v[144:145] op_sel:[0,0] op_sel_hi:[0,1]
	v_pk_mul_f32 v[142:143], v[58:59], v[142:143]
	v_pk_mul_f32 v[144:145], v[60:61], v[144:145]
	v_mul_f32_e32 v142, v255, v142
	v_mul_f32_e32 v143, v255, v143
	v_mul_f32_e32 v144, v255, v144
	v_mul_f32_e32 v145, v255, v145
	v_exp_f32_e32 v142, v142
	v_exp_f32_e32 v143, v143
	v_exp_f32_e32 v144, v144
	v_exp_f32_e32 v145, v145
	v_add_f32_e32 v142, 1.0, v142
	v_add_f32_e32 v143, 1.0, v143
	v_add_f32_e32 v144, 1.0, v144
	v_add_f32_e32 v145, 1.0, v145
	v_rcp_f32_e32 v142, v142
	v_rcp_f32_e32 v143, v143
	v_rcp_f32_e32 v144, v144
	v_rcp_f32_e32 v145, v145
	s_waitcnt vmcnt(13)
	v_lshlrev_b32_e32 v250, 16, v162
	v_and_b32_e32 v251, 0xffff0000, v162
	v_lshlrev_b32_e32 v252, 16, v163
	v_and_b32_e32 v253, 0xffff0000, v163
	v_pk_fma_f32 v[146:147], v[142:143], v[250:251], v[146:147]
	v_pk_fma_f32 v[148:149], v[144:145], v[252:253], v[148:149]
	global_store_dwordx4 v190, v[146:149], s[54:55] offset:0
	v_pk_mul_f32 v[138:139], v[242:243], v[138:139] op_sel:[0,0] op_sel_hi:[0,1]
	v_pk_mul_f32 v[140:141], v[242:243], v[140:141] op_sel:[0,0] op_sel_hi:[0,1]
	v_pk_mul_f32 v[138:139], v[66:67], v[138:139]
	v_pk_mul_f32 v[140:141], v[68:69], v[140:141]
	v_mul_f32_e32 v138, v255, v138
	v_mul_f32_e32 v139, v255, v139
	v_mul_f32_e32 v140, v255, v140
	v_mul_f32_e32 v141, v255, v141
	v_exp_f32_e32 v138, v138
	v_exp_f32_e32 v139, v139
	v_exp_f32_e32 v140, v140
	v_exp_f32_e32 v141, v141
	v_add_f32_e32 v138, 1.0, v138
	v_add_f32_e32 v139, 1.0, v139
	v_add_f32_e32 v140, 1.0, v140
	v_add_f32_e32 v141, 1.0, v141
	v_rcp_f32_e32 v138, v138
	v_rcp_f32_e32 v139, v139
	v_rcp_f32_e32 v140, v140
	v_rcp_f32_e32 v141, v141
	v_lshlrev_b32_e32 v250, 16, v164
	v_and_b32_e32 v251, 0xffff0000, v164
	v_lshlrev_b32_e32 v252, 16, v165
	v_and_b32_e32 v253, 0xffff0000, v165
	v_pk_fma_f32 v[150:151], v[138:139], v[250:251], v[150:151]
	v_pk_fma_f32 v[152:153], v[140:141], v[252:253], v[152:153]
	global_store_dwordx4 v190, v[150:153], s[54:55] offset:64
	v_pk_mul_f32 v[134:135], v[242:243], v[134:135] op_sel:[0,0] op_sel_hi:[0,1]
	v_pk_mul_f32 v[136:137], v[242:243], v[136:137] op_sel:[0,0] op_sel_hi:[0,1]
	v_pk_mul_f32 v[134:135], v[74:75], v[134:135]
	v_pk_mul_f32 v[136:137], v[76:77], v[136:137]
	v_mul_f32_e32 v134, v255, v134
	v_mul_f32_e32 v135, v255, v135
	v_mul_f32_e32 v136, v255, v136
	v_mul_f32_e32 v137, v255, v137
	v_exp_f32_e32 v134, v134
	v_exp_f32_e32 v135, v135
	v_exp_f32_e32 v136, v136
	v_exp_f32_e32 v137, v137
	v_add_f32_e32 v134, 1.0, v134
	v_add_f32_e32 v135, 1.0, v135
	v_add_f32_e32 v136, 1.0, v136
	v_add_f32_e32 v137, 1.0, v137
	v_rcp_f32_e32 v134, v134
	v_rcp_f32_e32 v135, v135
	v_rcp_f32_e32 v136, v136
	v_rcp_f32_e32 v137, v137
	s_waitcnt vmcnt(14)
	v_lshlrev_b32_e32 v250, 16, v178
	v_and_b32_e32 v251, 0xffff0000, v178
	v_lshlrev_b32_e32 v252, 16, v179
	v_and_b32_e32 v253, 0xffff0000, v179
	v_pk_fma_f32 v[154:155], v[134:135], v[250:251], v[154:155]
	v_pk_fma_f32 v[156:157], v[136:137], v[252:253], v[156:157]
	global_store_dwordx4 v190, v[154:157], s[54:55] offset:512
	v_pk_mul_f32 v[130:131], v[242:243], v[130:131] op_sel:[0,0] op_sel_hi:[0,1]
	v_pk_mul_f32 v[132:133], v[242:243], v[132:133] op_sel:[0,0] op_sel_hi:[0,1]
	v_pk_mul_f32 v[130:131], v[78:79], v[130:131]
	v_pk_mul_f32 v[132:133], v[80:81], v[132:133]
	v_mul_f32_e32 v130, v255, v130
	v_mul_f32_e32 v131, v255, v131
	v_mul_f32_e32 v132, v255, v132
	v_mul_f32_e32 v133, v255, v133
	v_exp_f32_e32 v130, v130
	v_exp_f32_e32 v131, v131
	v_exp_f32_e32 v132, v132
	v_exp_f32_e32 v133, v133
	v_add_f32_e32 v130, 1.0, v130
	v_add_f32_e32 v131, 1.0, v131
	v_add_f32_e32 v132, 1.0, v132
	v_add_f32_e32 v133, 1.0, v133
	v_rcp_f32_e32 v130, v130
	v_rcp_f32_e32 v131, v131
	v_rcp_f32_e32 v132, v132
	v_rcp_f32_e32 v133, v133
	v_lshlrev_b32_e32 v250, 16, v180
	v_and_b32_e32 v251, 0xffff0000, v180
	v_lshlrev_b32_e32 v252, 16, v181
	v_and_b32_e32 v253, 0xffff0000, v181
	v_pk_fma_f32 v[158:159], v[130:131], v[250:251], v[158:159]
	v_pk_fma_f32 v[160:161], v[132:133], v[252:253], v[160:161]
	global_store_dwordx4 v190, v[158:161], s[54:55] offset:576
	v_add_u32_e32 v194, 0xc0000, v190
	v_add_u32_e32 v195, 0x1800, v191
	global_load_dwordx4 v[146:149], v194, s[54:55] offset:0
	global_load_dwordx4 v[150:153], v194, s[54:55] offset:64
	global_load_dwordx4 v[154:157], v194, s[54:55] offset:512
	global_load_dwordx4 v[158:161], v194, s[54:55] offset:576
	global_load_dwordx4 v[162:165], v195, s[8:9] offset:0
	global_load_dwordx4 v[178:181], v195, s[8:9] offset:1024
	v_add_u32_e32 v194, 0x40000, v190
	v_pk_mul_f32 v[126:127], v[242:243], v[126:127] op_sel:[1,0] op_sel_hi:[1,1]
	v_pk_mul_f32 v[128:129], v[242:243], v[128:129] op_sel:[1,0] op_sel_hi:[1,1]
	v_pk_mul_f32 v[126:127], v[58:59], v[126:127]
	v_pk_mul_f32 v[128:129], v[60:61], v[128:129]
	v_mul_f32_e32 v126, v255, v126
	v_mul_f32_e32 v127, v255, v127
	v_mul_f32_e32 v128, v255, v128
	v_mul_f32_e32 v129, v255, v129
	v_exp_f32_e32 v126, v126
	v_exp_f32_e32 v127, v127
	v_exp_f32_e32 v128, v128
	v_exp_f32_e32 v129, v129
	v_add_f32_e32 v126, 1.0, v126
	v_add_f32_e32 v127, 1.0, v127
	v_add_f32_e32 v128, 1.0, v128
	v_add_f32_e32 v129, 1.0, v129
	v_rcp_f32_e32 v126, v126
	v_rcp_f32_e32 v127, v127
	v_rcp_f32_e32 v128, v128
	v_rcp_f32_e32 v129, v129
	s_waitcnt vmcnt(17)
; __device__ __forceinline__ unsigned cvt_pk_bf16(float lo, float hi) { unsigned r; asm volatile("s_nop 0\n\tv_cvt_pk_bf16_f32 %0, %1, %2" : "=v"(r) : "v"(lo), "v"(hi)); return r; }
; __device__ __forceinline__ f32x4 sig4(const f32x4 v) { return (f32x4){sigmoidf_(v[0]), sigmoidf_(v[1]), sigmoidf_(v[2]), sigmoidf_(v[3])}; }
;     __device__ __forceinline__ void operator()(const typename AccT<I8>::type (&acc)[2][2][4][2], const Unit& u, int wr, int wc, int fr, int fq) const {
;     ...
;         for (int s = 0; s < 8; ++s) { const int ai = s >> 2, m = s & 3; const int r = row0 + ai * HALF + m * 16; const size_t off = (size_t)r * 4096 + col0;
;                 if (s + 1 < 8) load_row(nxt, (size_t)(row0 + ((s + 1) >> 2) * HALF + ((s + 1) & 3) * 16) * 4096 + col0);
;                 const float rs = rsv[s];
;                 float ss = 0.f, mx = 0.f;
; #pragma unroll
;                 for (int bj = 0; bj < 2; ++bj)
; #pragma unroll
;                     for (int n = 0; n < 2; ++n) { const size_t o = off + bj * HALF + n * 16; const f32x4 b = cur.b[bj][n]; f32x4 v;
;                         if constexpr (I8) v = __builtin_convertvector(acc[ai][bj][m][n], f32x4) * rs * sv[bj][n]; else v = acc[ai][bj][m][n];
;                         if (MODE == 1) { const u32x2 pw = cur.pw[bj][n]; const f32x4 pp = (f32x4){bf_lo(pw.x), bf_hi(pw.x), bf_lo(pw.y), bf_hi(pw.y)}; v = sig4(I8 ? v : v * rs) * pp; }
;                         const f32x4 x = b + v; *(f32x4*)(out + o) = x;
;                         if (MODE == 0 && XB) { u32x2 w; w.x = cvt_pk_bf16(x[0], x[1]); w.y = cvt_pk_bf16(x[2], x[3]); *(u32x2*)(XB + o) = w; ss += (x[0] * x[0] + x[1] * x[1]) + (x[2] * x[2] + x[3] * x[3]);
;                             if (RM) mx = fmaxf(fmaxf(mx, fmaxf(fabsf(x[0]), fabsf(x[1]))), fmaxf(fabsf(x[2]), fabsf(x[3]))); } }
;                 if (MODE == 0 && XB) { ss += __shfl_xor(ss, 16); ss += __shfl_xor(ss, 32); if (fq == 0) unsafeAtomicAdd(SS + r, ss);
;                     if (RM) { mx = fmaxf(mx, __shfl_xor(mx, 16)); mx = fmaxf(mx, __shfl_xor(mx, 32)); if (fq == 0) atomicMax(RM + r, __builtin_bit_cast(unsigned, mx)); } }
;                 cur = nxt; }
	v_lshlrev_b32_e32 v250, 16, v184
	v_and_b32_e32 v251, 0xffff0000, v184
	v_lshlrev_b32_e32 v252, 16, v185
	v_and_b32_e32 v253, 0xffff0000, v185
	v_pk_fma_f32 v[198:199], v[126:127], v[250:251], v[198:199]
	v_pk_fma_f32 v[200:201], v[128:129], v[252:253], v[200:201]
	global_store_dwordx4 v194, v[198:201], s[54:55] offset:0
	v_pk_mul_f32 v[122:123], v[242:243], v[122:123] op_sel:[1,0] op_sel_hi:[1,1]
	v_pk_mul_f32 v[124:125], v[242:243], v[124:125] op_sel:[1,0] op_sel_hi:[1,1]
	v_pk_mul_f32 v[122:123], v[66:67], v[122:123]
	v_pk_mul_f32 v[124:125], v[68:69], v[124:125]
	v_mul_f32_e32 v122, v255, v122
	v_mul_f32_e32 v123, v255, v123
	v_mul_f32_e32 v124, v255, v124
	v_mul_f32_e32 v125, v255, v125
	v_exp_f32_e32 v122, v122
	v_exp_f32_e32 v123, v123
	v_exp_f32_e32 v124, v124
	v_exp_f32_e32 v125, v125
	v_add_f32_e32 v122, 1.0, v122
	v_add_f32_e32 v123, 1.0, v123
	v_add_f32_e32 v124, 1.0, v124
	v_add_f32_e32 v125, 1.0, v125
	v_rcp_f32_e32 v122, v122
	v_rcp_f32_e32 v123, v123
	v_rcp_f32_e32 v124, v124
	v_rcp_f32_e32 v125, v125
	v_lshlrev_b32_e32 v250, 16, v186
	v_and_b32_e32 v251, 0xffff0000, v186
	v_lshlrev_b32_e32 v252, 16, v187
	v_and_b32_e32 v253, 0xffff0000, v187
	v_pk_fma_f32 v[202:203], v[122:123], v[250:251], v[202:203]
	v_pk_fma_f32 v[204:205], v[124:125], v[252:253], v[204:205]
	global_store_dwordx4 v194, v[202:205], s[54:55] offset:64
	v_pk_mul_f32 v[118:119], v[242:243], v[118:119] op_sel:[1,0] op_sel_hi:[1,1]
	v_pk_mul_f32 v[120:121], v[242:243], v[120:121] op_sel:[1,0] op_sel_hi:[1,1]
	v_pk_mul_f32 v[118:119], v[74:75], v[118:119]
	v_pk_mul_f32 v[120:121], v[76:77], v[120:121]
	v_mul_f32_e32 v118, v255, v118
	v_mul_f32_e32 v119, v255, v119
	v_mul_f32_e32 v120, v255, v120
	v_mul_f32_e32 v121, v255, v121
	v_exp_f32_e32 v118, v118
	v_exp_f32_e32 v119, v119
	v_exp_f32_e32 v120, v120
	v_exp_f32_e32 v121, v121
	v_add_f32_e32 v118, 1.0, v118
	v_add_f32_e32 v119, 1.0, v119
	v_add_f32_e32 v120, 1.0, v120
	v_add_f32_e32 v121, 1.0, v121
	v_rcp_f32_e32 v118, v118
	v_rcp_f32_e32 v119, v119
	v_rcp_f32_e32 v120, v120
	v_rcp_f32_e32 v121, v121
	s_waitcnt vmcnt(18)
	v_lshlrev_b32_e32 v250, 16, v214
	v_and_b32_e32 v251, 0xffff0000, v214
	v_lshlrev_b32_e32 v252, 16, v215
	v_and_b32_e32 v253, 0xffff0000, v215
	v_pk_fma_f32 v[206:207], v[118:119], v[250:251], v[206:207]
	v_pk_fma_f32 v[208:209], v[120:121], v[252:253], v[208:209]
	global_store_dwordx4 v194, v[206:209], s[54:55] offset:512
	v_pk_mul_f32 v[114:115], v[242:243], v[114:115] op_sel:[1,0] op_sel_hi:[1,1]
	v_pk_mul_f32 v[116:117], v[242:243], v[116:117] op_sel:[1,0] op_sel_hi:[1,1]
	v_pk_mul_f32 v[114:115], v[78:79], v[114:115]
	v_pk_mul_f32 v[116:117], v[80:81], v[116:117]
	v_mul_f32_e32 v114, v255, v114
	v_mul_f32_e32 v115, v255, v115
	v_mul_f32_e32 v116, v255, v116
	v_mul_f32_e32 v117, v255, v117
	v_exp_f32_e32 v114, v114
	v_exp_f32_e32 v115, v115
	v_exp_f32_e32 v116, v116
	v_exp_f32_e32 v117, v117
	v_add_f32_e32 v114, 1.0, v114
	v_add_f32_e32 v115, 1.0, v115
	v_add_f32_e32 v116, 1.0, v116
	v_add_f32_e32 v117, 1.0, v117
	v_rcp_f32_e32 v114, v114
	v_rcp_f32_e32 v115, v115
	v_rcp_f32_e32 v116, v116
	v_rcp_f32_e32 v117, v117
	v_lshlrev_b32_e32 v250, 16, v216
	v_and_b32_e32 v251, 0xffff0000, v216
	v_lshlrev_b32_e32 v252, 16, v217
	v_and_b32_e32 v253, 0xffff0000, v217
	v_pk_fma_f32 v[210:211], v[114:115], v[250:251], v[210:211]
	v_pk_fma_f32 v[212:213], v[116:117], v[252:253], v[212:213]
	global_store_dwordx4 v194, v[210:213], s[54:55] offset:576
	v_add_u32_e32 v194, 0x200000, v190
	v_add_u32_e32 v195, 0x2000, v191
	global_load_dwordx4 v[198:201], v194, s[54:55] offset:0
	global_load_dwordx4 v[202:205], v194, s[54:55] offset:64
	global_load_dwordx4 v[206:209], v194, s[54:55] offset:512
	global_load_dwordx4 v[210:213], v194, s[54:55] offset:576
	global_load_dwordx4 v[184:187], v195, s[8:9] offset:0
	global_load_dwordx4 v[214:217], v195, s[8:9] offset:1024
	v_add_u32_e32 v194, 0x240000, v190
	v_add_u32_e32 v195, 0x2800, v191
	global_load_dwordx4 v[142:145], v194, s[54:55] offset:0
	global_load_dwordx4 v[138:141], v194, s[54:55] offset:64
	global_load_dwordx4 v[134:137], v194, s[54:55] offset:512
	global_load_dwordx4 v[130:133], v194, s[54:55] offset:576
	global_load_dwordx4 v[126:129], v195, s[8:9] offset:0
	global_load_dwordx4 v[122:125], v195, s[8:9] offset:1024
	v_add_u32_e32 v194, 0x80000, v190
	v_pk_mul_f32 v[110:111], v[244:245], v[110:111] op_sel:[0,0] op_sel_hi:[0,1]
	v_pk_mul_f32 v[112:113], v[244:245], v[112:113] op_sel:[0,0] op_sel_hi:[0,1]
	v_pk_mul_f32 v[110:111], v[58:59], v[110:111]
	v_pk_mul_f32 v[112:113], v[60:61], v[112:113]
	v_mul_f32_e32 v110, v255, v110
	v_mul_f32_e32 v111, v255, v111
	v_mul_f32_e32 v112, v255, v112
	v_mul_f32_e32 v113, v255, v113
	v_exp_f32_e32 v110, v110
	v_exp_f32_e32 v111, v111
	v_exp_f32_e32 v112, v112
	v_exp_f32_e32 v113, v113
	v_add_f32_e32 v110, 1.0, v110
	v_add_f32_e32 v111, 1.0, v111
	v_add_f32_e32 v112, 1.0, v112
	v_add_f32_e32 v113, 1.0, v113
	v_rcp_f32_e32 v110, v110
	v_rcp_f32_e32 v111, v111
	v_rcp_f32_e32 v112, v112
	v_rcp_f32_e32 v113, v113
	s_waitcnt vmcnt(27)
; __device__ __forceinline__ unsigned cvt_pk_bf16(float lo, float hi) { unsigned r; asm volatile("s_nop 0\n\tv_cvt_pk_bf16_f32 %0, %1, %2" : "=v"(r) : "v"(lo), "v"(hi)); return r; }
; __device__ __forceinline__ f32x4 sig4(const f32x4 v) { return (f32x4){sigmoidf_(v[0]), sigmoidf_(v[1]), sigmoidf_(v[2]), sigmoidf_(v[3])}; }
;     __device__ __forceinline__ void operator()(const typename AccT<I8>::type (&acc)[2][2][4][2], const Unit& u, int wr, int wc, int fr, int fq) const {
;     ...
;         for (int s = 0; s < 8; ++s) { const int ai = s >> 2, m = s & 3; const int r = row0 + ai * HALF + m * 16; const size_t off = (size_t)r * 4096 + col0;
;                 if (s + 1 < 8) load_row(nxt, (size_t)(row0 + ((s + 1) >> 2) * HALF + ((s + 1) & 3) * 16) * 4096 + col0);
;                 const float rs = rsv[s];
;                 float ss = 0.f, mx = 0.f;
; #pragma unroll
;                 for (int bj = 0; bj < 2; ++bj)
; #pragma unroll
;                     for (int n = 0; n < 2; ++n) { const size_t o = off + bj * HALF + n * 16; const f32x4 b = cur.b[bj][n]; f32x4 v;
;                         if constexpr (I8) v = __builtin_convertvector(acc[ai][bj][m][n], f32x4) * rs * sv[bj][n]; else v = acc[ai][bj][m][n];
;                         if (MODE == 1) { const u32x2 pw = cur.pw[bj][n]; const f32x4 pp = (f32x4){bf_lo(pw.x), bf_hi(pw.x), bf_lo(pw.y), bf_hi(pw.y)}; v = sig4(I8 ? v : v * rs) * pp; }
;                         const f32x4 x = b + v; *(f32x4*)(out + o) = x;
;                         if (MODE == 0 && XB) { u32x2 w; w.x = cvt_pk_bf16(x[0], x[1]); w.y = cvt_pk_bf16(x[2], x[3]); *(u32x2*)(XB + o) = w; ss += (x[0] * x[0] + x[1] * x[1]) + (x[2] * x[2] + x[3] * x[3]);
;                             if (RM) mx = fmaxf(fmaxf(mx, fmaxf(fabsf(x[0]), fabsf(x[1]))), fmaxf(fabsf(x[2]), fabsf(x[3]))); } }
;                 if (MODE == 0 && XB) { ss += __shfl_xor(ss, 16); ss += __shfl_xor(ss, 32); if (fq == 0) unsafeAtomicAdd(SS + r, ss);
;                     if (RM) { mx = fmaxf(mx, __shfl_xor(mx, 16)); mx = fmaxf(mx, __shfl_xor(mx, 32)); if (fq == 0) atomicMax(RM + r, __builtin_bit_cast(unsigned, mx)); } }
;                 cur = nxt; }
	v_lshlrev_b32_e32 v250, 16, v234
	v_and_b32_e32 v251, 0xffff0000, v234
	v_lshlrev_b32_e32 v252, 16, v235
	v_and_b32_e32 v253, 0xffff0000, v235
	v_pk_fma_f32 v[218:219], v[110:111], v[250:251], v[218:219]
	v_pk_fma_f32 v[220:221], v[112:113], v[252:253], v[220:221]
	global_store_dwordx4 v194, v[218:221], s[54:55] offset:0
	v_pk_mul_f32 v[106:107], v[244:245], v[106:107] op_sel:[0,0] op_sel_hi:[0,1]
	v_pk_mul_f32 v[108:109], v[244:245], v[108:109] op_sel:[0,0] op_sel_hi:[0,1]
	v_pk_mul_f32 v[106:107], v[66:67], v[106:107]
	v_pk_mul_f32 v[108:109], v[68:69], v[108:109]
	v_mul_f32_e32 v106, v255, v106
	v_mul_f32_e32 v107, v255, v107
	v_mul_f32_e32 v108, v255, v108
	v_mul_f32_e32 v109, v255, v109
	v_exp_f32_e32 v106, v106
	v_exp_f32_e32 v107, v107
	v_exp_f32_e32 v108, v108
	v_exp_f32_e32 v109, v109
	v_add_f32_e32 v106, 1.0, v106
	v_add_f32_e32 v107, 1.0, v107
	v_add_f32_e32 v108, 1.0, v108
	v_add_f32_e32 v109, 1.0, v109
	v_rcp_f32_e32 v106, v106
	v_rcp_f32_e32 v107, v107
	v_rcp_f32_e32 v108, v108
	v_rcp_f32_e32 v109, v109
	v_lshlrev_b32_e32 v250, 16, v236
	v_and_b32_e32 v251, 0xffff0000, v236
	v_lshlrev_b32_e32 v252, 16, v237
	v_and_b32_e32 v253, 0xffff0000, v237
	v_pk_fma_f32 v[222:223], v[106:107], v[250:251], v[222:223]
	v_pk_fma_f32 v[224:225], v[108:109], v[252:253], v[224:225]
	global_store_dwordx4 v194, v[222:225], s[54:55] offset:64
	v_pk_mul_f32 v[102:103], v[244:245], v[102:103] op_sel:[0,0] op_sel_hi:[0,1]
	v_pk_mul_f32 v[104:105], v[244:245], v[104:105] op_sel:[0,0] op_sel_hi:[0,1]
	v_pk_mul_f32 v[102:103], v[74:75], v[102:103]
	v_pk_mul_f32 v[104:105], v[76:77], v[104:105]
	v_mul_f32_e32 v102, v255, v102
	v_mul_f32_e32 v103, v255, v103
	v_mul_f32_e32 v104, v255, v104
	v_mul_f32_e32 v105, v255, v105
	v_exp_f32_e32 v102, v102
	v_exp_f32_e32 v103, v103
	v_exp_f32_e32 v104, v104
	v_exp_f32_e32 v105, v105
	v_add_f32_e32 v102, 1.0, v102
	v_add_f32_e32 v103, 1.0, v103
	v_add_f32_e32 v104, 1.0, v104
	v_add_f32_e32 v105, 1.0, v105
	v_rcp_f32_e32 v102, v102
	v_rcp_f32_e32 v103, v103
	v_rcp_f32_e32 v104, v104
	v_rcp_f32_e32 v105, v105
	s_waitcnt vmcnt(28)
	v_lshlrev_b32_e32 v250, 16, v238
	v_and_b32_e32 v251, 0xffff0000, v238
	v_lshlrev_b32_e32 v252, 16, v239
	v_and_b32_e32 v253, 0xffff0000, v239
	v_pk_fma_f32 v[226:227], v[102:103], v[250:251], v[226:227]
	v_pk_fma_f32 v[228:229], v[104:105], v[252:253], v[228:229]
	global_store_dwordx4 v194, v[226:229], s[54:55] offset:512
	v_pk_mul_f32 v[98:99], v[244:245], v[98:99] op_sel:[0,0] op_sel_hi:[0,1]
	v_pk_mul_f32 v[100:101], v[244:245], v[100:101] op_sel:[0,0] op_sel_hi:[0,1]
	v_pk_mul_f32 v[98:99], v[78:79], v[98:99]
	v_pk_mul_f32 v[100:101], v[80:81], v[100:101]
	v_mul_f32_e32 v98, v255, v98
	v_mul_f32_e32 v99, v255, v99
	v_mul_f32_e32 v100, v255, v100
	v_mul_f32_e32 v101, v255, v101
	v_exp_f32_e32 v98, v98
	v_exp_f32_e32 v99, v99
	v_exp_f32_e32 v100, v100
	v_exp_f32_e32 v101, v101
	v_add_f32_e32 v98, 1.0, v98
	v_add_f32_e32 v99, 1.0, v99
	v_add_f32_e32 v100, 1.0, v100
	v_add_f32_e32 v101, 1.0, v101
	v_rcp_f32_e32 v98, v98
	v_rcp_f32_e32 v99, v99
	v_rcp_f32_e32 v100, v100
	v_rcp_f32_e32 v101, v101
	v_lshlrev_b32_e32 v250, 16, v240
	v_and_b32_e32 v251, 0xffff0000, v240
	v_lshlrev_b32_e32 v252, 16, v241
	v_and_b32_e32 v253, 0xffff0000, v241
	v_pk_fma_f32 v[230:231], v[98:99], v[250:251], v[230:231]
	v_pk_fma_f32 v[232:233], v[100:101], v[252:253], v[232:233]
	global_store_dwordx4 v194, v[230:233], s[54:55] offset:576
	v_add_u32_e32 v194, 0x280000, v190
	v_add_u32_e32 v195, 0x3000, v191
	global_load_dwordx4 v[218:221], v194, s[54:55] offset:0
	global_load_dwordx4 v[222:225], v194, s[54:55] offset:64
	global_load_dwordx4 v[226:229], v194, s[54:55] offset:512
	global_load_dwordx4 v[230:233], v194, s[54:55] offset:576
	global_load_dwordx4 v[234:237], v195, s[8:9] offset:0
	global_load_dwordx4 v[238:241], v195, s[8:9] offset:1024
	v_add_u32_e32 v194, 0x2c0000, v190
	v_add_u32_e32 v195, 0x3800, v191
	global_load_dwordx4 v[110:113], v194, s[54:55] offset:0
	global_load_dwordx4 v[106:109], v194, s[54:55] offset:64
	global_load_dwordx4 v[102:105], v194, s[54:55] offset:512
	global_load_dwordx4 v[98:101], v194, s[54:55] offset:576
	global_load_dwordx4 v[118:121], v195, s[8:9] offset:0
	global_load_dwordx4 v[114:117], v195, s[8:9] offset:1024
	v_add_u32_e32 v194, 0xc0000, v190
	v_pk_mul_f32 v[94:95], v[244:245], v[94:95] op_sel:[1,0] op_sel_hi:[1,1]
	v_pk_mul_f32 v[96:97], v[244:245], v[96:97] op_sel:[1,0] op_sel_hi:[1,1]
	v_pk_mul_f32 v[94:95], v[58:59], v[94:95]
	v_pk_mul_f32 v[96:97], v[60:61], v[96:97]
	v_mul_f32_e32 v94, v255, v94
	v_mul_f32_e32 v95, v255, v95
	v_mul_f32_e32 v96, v255, v96
	v_mul_f32_e32 v97, v255, v97
	v_exp_f32_e32 v94, v94
	v_exp_f32_e32 v95, v95
	v_exp_f32_e32 v96, v96
	v_exp_f32_e32 v97, v97
	v_add_f32_e32 v94, 1.0, v94
	v_add_f32_e32 v95, 1.0, v95
	v_add_f32_e32 v96, 1.0, v96
	v_add_f32_e32 v97, 1.0, v97
	v_rcp_f32_e32 v94, v94
	v_rcp_f32_e32 v95, v95
	v_rcp_f32_e32 v96, v96
	v_rcp_f32_e32 v97, v97
	s_waitcnt vmcnt(33)
; __device__ __forceinline__ unsigned cvt_pk_bf16(float lo, float hi) { unsigned r; asm volatile("s_nop 0\n\tv_cvt_pk_bf16_f32 %0, %1, %2" : "=v"(r) : "v"(lo), "v"(hi)); return r; }
; __device__ __forceinline__ f32x4 sig4(const f32x4 v) { return (f32x4){sigmoidf_(v[0]), sigmoidf_(v[1]), sigmoidf_(v[2]), sigmoidf_(v[3])}; }
;     __device__ __forceinline__ void operator()(const typename AccT<I8>::type (&acc)[2][2][4][2], const Unit& u, int wr, int wc, int fr, int fq) const {
;     ...
;         for (int s = 0; s < 8; ++s) { const int ai = s >> 2, m = s & 3; const int r = row0 + ai * HALF + m * 16; const size_t off = (size_t)r * 4096 + col0;
;                 if (s + 1 < 8) load_row(nxt, (size_t)(row0 + ((s + 1) >> 2) * HALF + ((s + 1) & 3) * 16) * 4096 + col0);
;                 const float rs = rsv[s];
;                 float ss = 0.f, mx = 0.f;
; #pragma unroll
;                 for (int bj = 0; bj < 2; ++bj)
; #pragma unroll
;                     for (int n = 0; n < 2; ++n) { const size_t o = off + bj * HALF + n * 16; const f32x4 b = cur.b[bj][n]; f32x4 v;
;                         if constexpr (I8) v = __builtin_convertvector(acc[ai][bj][m][n], f32x4) * rs * sv[bj][n]; else v = acc[ai][bj][m][n];
;                         if (MODE == 1) { const u32x2 pw = cur.pw[bj][n]; const f32x4 pp = (f32x4){bf_lo(pw.x), bf_hi(pw.x), bf_lo(pw.y), bf_hi(pw.y)}; v = sig4(I8 ? v : v * rs) * pp; }
;                         const f32x4 x = b + v; *(f32x4*)(out + o) = x;
;                         if (MODE == 0 && XB) { u32x2 w; w.x = cvt_pk_bf16(x[0], x[1]); w.y = cvt_pk_bf16(x[2], x[3]); *(u32x2*)(XB + o) = w; ss += (x[0] * x[0] + x[1] * x[1]) + (x[2] * x[2] + x[3] * x[3]);
;                             if (RM) mx = fmaxf(fmaxf(mx, fmaxf(fabsf(x[0]), fabsf(x[1]))), fmaxf(fabsf(x[2]), fabsf(x[3]))); } }
;                 if (MODE == 0 && XB) { ss += __shfl_xor(ss, 16); ss += __shfl_xor(ss, 32); if (fq == 0) unsafeAtomicAdd(SS + r, ss);
;                     if (RM) { mx = fmaxf(mx, __shfl_xor(mx, 16)); mx = fmaxf(mx, __shfl_xor(mx, 32)); if (fq == 0) atomicMax(RM + r, __builtin_bit_cast(unsigned, mx)); } }
;                 cur = nxt; }
	v_lshlrev_b32_e32 v250, 16, v162
	v_and_b32_e32 v251, 0xffff0000, v162
	v_lshlrev_b32_e32 v252, 16, v163
	v_and_b32_e32 v253, 0xffff0000, v163
	v_pk_fma_f32 v[146:147], v[94:95], v[250:251], v[146:147]
	v_pk_fma_f32 v[148:149], v[96:97], v[252:253], v[148:149]
	global_store_dwordx4 v194, v[146:149], s[54:55] offset:0
	v_pk_mul_f32 v[90:91], v[244:245], v[90:91] op_sel:[1,0] op_sel_hi:[1,1]
	v_pk_mul_f32 v[92:93], v[244:245], v[92:93] op_sel:[1,0] op_sel_hi:[1,1]
	v_pk_mul_f32 v[90:91], v[66:67], v[90:91]
	v_pk_mul_f32 v[92:93], v[68:69], v[92:93]
	v_mul_f32_e32 v90, v255, v90
	v_mul_f32_e32 v91, v255, v91
	v_mul_f32_e32 v92, v255, v92
	v_mul_f32_e32 v93, v255, v93
	v_exp_f32_e32 v90, v90
	v_exp_f32_e32 v91, v91
	v_exp_f32_e32 v92, v92
	v_exp_f32_e32 v93, v93
	v_add_f32_e32 v90, 1.0, v90
	v_add_f32_e32 v91, 1.0, v91
	v_add_f32_e32 v92, 1.0, v92
	v_add_f32_e32 v93, 1.0, v93
	v_rcp_f32_e32 v90, v90
	v_rcp_f32_e32 v91, v91
	v_rcp_f32_e32 v92, v92
	v_rcp_f32_e32 v93, v93
	v_lshlrev_b32_e32 v250, 16, v164
	v_and_b32_e32 v251, 0xffff0000, v164
	v_lshlrev_b32_e32 v252, 16, v165
	v_and_b32_e32 v253, 0xffff0000, v165
	v_pk_fma_f32 v[150:151], v[90:91], v[250:251], v[150:151]
	v_pk_fma_f32 v[152:153], v[92:93], v[252:253], v[152:153]
	global_store_dwordx4 v194, v[150:153], s[54:55] offset:64
	v_pk_mul_f32 v[86:87], v[244:245], v[86:87] op_sel:[1,0] op_sel_hi:[1,1]
	v_pk_mul_f32 v[88:89], v[244:245], v[88:89] op_sel:[1,0] op_sel_hi:[1,1]
	v_pk_mul_f32 v[86:87], v[74:75], v[86:87]
	v_pk_mul_f32 v[88:89], v[76:77], v[88:89]
	v_mul_f32_e32 v86, v255, v86
	v_mul_f32_e32 v87, v255, v87
	v_mul_f32_e32 v88, v255, v88
	v_mul_f32_e32 v89, v255, v89
	v_exp_f32_e32 v86, v86
	v_exp_f32_e32 v87, v87
	v_exp_f32_e32 v88, v88
	v_exp_f32_e32 v89, v89
	v_add_f32_e32 v86, 1.0, v86
	v_add_f32_e32 v87, 1.0, v87
	v_add_f32_e32 v88, 1.0, v88
	v_add_f32_e32 v89, 1.0, v89
	v_rcp_f32_e32 v86, v86
	v_rcp_f32_e32 v87, v87
	v_rcp_f32_e32 v88, v88
	v_rcp_f32_e32 v89, v89
	s_waitcnt vmcnt(34)
	v_lshlrev_b32_e32 v250, 16, v178
	v_and_b32_e32 v251, 0xffff0000, v178
	v_lshlrev_b32_e32 v252, 16, v179
	v_and_b32_e32 v253, 0xffff0000, v179
	v_pk_fma_f32 v[154:155], v[86:87], v[250:251], v[154:155]
	v_pk_fma_f32 v[156:157], v[88:89], v[252:253], v[156:157]
	global_store_dwordx4 v194, v[154:157], s[54:55] offset:512
	v_pk_mul_f32 v[82:83], v[244:245], v[82:83] op_sel:[1,0] op_sel_hi:[1,1]
	v_pk_mul_f32 v[84:85], v[244:245], v[84:85] op_sel:[1,0] op_sel_hi:[1,1]
	v_pk_mul_f32 v[82:83], v[78:79], v[82:83]
	v_pk_mul_f32 v[84:85], v[80:81], v[84:85]
	v_mul_f32_e32 v82, v255, v82
	v_mul_f32_e32 v83, v255, v83
	v_mul_f32_e32 v84, v255, v84
	v_mul_f32_e32 v85, v255, v85
	v_exp_f32_e32 v82, v82
	v_exp_f32_e32 v83, v83
	v_exp_f32_e32 v84, v84
	v_exp_f32_e32 v85, v85
	v_add_f32_e32 v82, 1.0, v82
	v_add_f32_e32 v83, 1.0, v83
	v_add_f32_e32 v84, 1.0, v84
	v_add_f32_e32 v85, 1.0, v85
	v_rcp_f32_e32 v82, v82
	v_rcp_f32_e32 v83, v83
	v_rcp_f32_e32 v84, v84
	v_rcp_f32_e32 v85, v85
	v_lshlrev_b32_e32 v250, 16, v180
	v_and_b32_e32 v251, 0xffff0000, v180
	v_lshlrev_b32_e32 v252, 16, v181
	v_and_b32_e32 v253, 0xffff0000, v181
	v_pk_fma_f32 v[158:159], v[82:83], v[250:251], v[158:159]
	v_pk_fma_f32 v[160:161], v[84:85], v[252:253], v[160:161]
	global_store_dwordx4 v194, v[158:161], s[54:55] offset:576
	v_add_u32_e32 v194, 0x200000, v190
	v_pk_mul_f32 v[70:71], v[246:247], v[70:71] op_sel:[0,0] op_sel_hi:[0,1]
	v_pk_mul_f32 v[72:73], v[246:247], v[72:73] op_sel:[0,0] op_sel_hi:[0,1]
	v_pk_mul_f32 v[70:71], v[58:59], v[70:71]
	v_pk_mul_f32 v[72:73], v[60:61], v[72:73]
	v_mul_f32_e32 v70, v255, v70
	v_mul_f32_e32 v71, v255, v71
	v_mul_f32_e32 v72, v255, v72
	v_mul_f32_e32 v73, v255, v73
	v_exp_f32_e32 v70, v70
	v_exp_f32_e32 v71, v71
	v_exp_f32_e32 v72, v72
	v_exp_f32_e32 v73, v73
	v_add_f32_e32 v70, 1.0, v70
	v_add_f32_e32 v71, 1.0, v71
	v_add_f32_e32 v72, 1.0, v72
	v_add_f32_e32 v73, 1.0, v73
	v_rcp_f32_e32 v70, v70
	v_rcp_f32_e32 v71, v71
	v_rcp_f32_e32 v72, v72
	v_rcp_f32_e32 v73, v73
	s_waitcnt vmcnt(27)
	v_lshlrev_b32_e32 v250, 16, v184
	v_and_b32_e32 v251, 0xffff0000, v184
	v_lshlrev_b32_e32 v252, 16, v185
	v_and_b32_e32 v253, 0xffff0000, v185
	v_pk_fma_f32 v[198:199], v[70:71], v[250:251], v[198:199]
	v_pk_fma_f32 v[200:201], v[72:73], v[252:253], v[200:201]
	global_store_dwordx4 v194, v[198:201], s[54:55] offset:0
	v_pk_mul_f32 v[62:63], v[246:247], v[62:63] op_sel:[0,0] op_sel_hi:[0,1]
	v_pk_mul_f32 v[64:65], v[246:247], v[64:65] op_sel:[0,0] op_sel_hi:[0,1]
	v_pk_mul_f32 v[62:63], v[66:67], v[62:63]
	v_pk_mul_f32 v[64:65], v[68:69], v[64:65]
	v_mul_f32_e32 v62, v255, v62
	v_mul_f32_e32 v63, v255, v63
	v_mul_f32_e32 v64, v255, v64
	v_mul_f32_e32 v65, v255, v65
	v_exp_f32_e32 v62, v62
	v_exp_f32_e32 v63, v63
	v_exp_f32_e32 v64, v64
	v_exp_f32_e32 v65, v65
	v_add_f32_e32 v62, 1.0, v62
	v_add_f32_e32 v63, 1.0, v63
	v_add_f32_e32 v64, 1.0, v64
	v_add_f32_e32 v65, 1.0, v65
	v_rcp_f32_e32 v62, v62
	v_rcp_f32_e32 v63, v63
	v_rcp_f32_e32 v64, v64
	v_rcp_f32_e32 v65, v65
	v_lshlrev_b32_e32 v250, 16, v186
	v_and_b32_e32 v251, 0xffff0000, v186
	v_lshlrev_b32_e32 v252, 16, v187
	v_and_b32_e32 v253, 0xffff0000, v187
	v_pk_fma_f32 v[202:203], v[62:63], v[250:251], v[202:203]
	v_pk_fma_f32 v[204:205], v[64:65], v[252:253], v[204:205]
	global_store_dwordx4 v194, v[202:205], s[54:55] offset:64
	v_pk_mul_f32 v[54:55], v[246:247], v[54:55] op_sel:[0,0] op_sel_hi:[0,1]
	v_pk_mul_f32 v[56:57], v[246:247], v[56:57] op_sel:[0,0] op_sel_hi:[0,1]
	v_pk_mul_f32 v[54:55], v[74:75], v[54:55]
	v_pk_mul_f32 v[56:57], v[76:77], v[56:57]
	v_mul_f32_e32 v54, v255, v54
	v_mul_f32_e32 v55, v255, v55
	v_mul_f32_e32 v56, v255, v56
	v_mul_f32_e32 v57, v255, v57
	v_exp_f32_e32 v54, v54
	v_exp_f32_e32 v55, v55
	v_exp_f32_e32 v56, v56
	v_exp_f32_e32 v57, v57
	v_add_f32_e32 v54, 1.0, v54
	v_add_f32_e32 v55, 1.0, v55
	v_add_f32_e32 v56, 1.0, v56
	v_add_f32_e32 v57, 1.0, v57
	v_rcp_f32_e32 v54, v54
	v_rcp_f32_e32 v55, v55
	v_rcp_f32_e32 v56, v56
	v_rcp_f32_e32 v57, v57
	s_waitcnt vmcnt(28)
; __device__ __forceinline__ f32x4 sig4(const f32x4 v) { return (f32x4){sigmoidf_(v[0]), sigmoidf_(v[1]), sigmoidf_(v[2]), sigmoidf_(v[3])}; }
;     __device__ __forceinline__ void operator()(const typename AccT<I8>::type (&acc)[2][2][4][2], const Unit& u, int wr, int wc, int fr, int fq) const {
;     ...
;         for (int s = 0; s < 8; ++s) { const int ai = s >> 2, m = s & 3; const int r = row0 + ai * HALF + m * 16; const size_t off = (size_t)r * 4096 + col0;
;                 if (s + 1 < 8) load_row(nxt, (size_t)(row0 + ((s + 1) >> 2) * HALF + ((s + 1) & 3) * 16) * 4096 + col0);
;                 const float rs = rsv[s];
;                 float ss = 0.f, mx = 0.f;
; #pragma unroll
;                 for (int bj = 0; bj < 2; ++bj)
; #pragma unroll
;                     for (int n = 0; n < 2; ++n) { const size_t o = off + bj * HALF + n * 16; const f32x4 b = cur.b[bj][n]; f32x4 v;
;                         if constexpr (I8) v = __builtin_convertvector(acc[ai][bj][m][n], f32x4) * rs * sv[bj][n]; else v = acc[ai][bj][m][n];
;                         if (MODE == 1) { const u32x2 pw = cur.pw[bj][n]; const f32x4 pp = (f32x4){bf_lo(pw.x), bf_hi(pw.x), bf_lo(pw.y), bf_hi(pw.y)}; v = sig4(I8 ? v : v * rs) * pp; }
;                         const f32x4 x = b + v; *(f32x4*)(out + o) = x;
	v_lshlrev_b32_e32 v250, 16, v214
	v_and_b32_e32 v251, 0xffff0000, v214
	v_lshlrev_b32_e32 v252, 16, v215
	v_and_b32_e32 v253, 0xffff0000, v215
	v_pk_fma_f32 v[206:207], v[54:55], v[250:251], v[206:207]
	v_pk_fma_f32 v[208:209], v[56:57], v[252:253], v[208:209]
	global_store_dwordx4 v194, v[206:209], s[54:55] offset:512
	v_pk_mul_f32 v[50:51], v[246:247], v[50:51] op_sel:[0,0] op_sel_hi:[0,1]
	v_pk_mul_f32 v[52:53], v[246:247], v[52:53] op_sel:[0,0] op_sel_hi:[0,1]
	v_pk_mul_f32 v[50:51], v[78:79], v[50:51]
	v_pk_mul_f32 v[52:53], v[80:81], v[52:53]
	v_mul_f32_e32 v50, v255, v50
	v_mul_f32_e32 v51, v255, v51
	v_mul_f32_e32 v52, v255, v52
	v_mul_f32_e32 v53, v255, v53
	v_exp_f32_e32 v50, v50
	v_exp_f32_e32 v51, v51
	v_exp_f32_e32 v52, v52
	v_exp_f32_e32 v53, v53
	v_add_f32_e32 v50, 1.0, v50
	v_add_f32_e32 v51, 1.0, v51
	v_add_f32_e32 v52, 1.0, v52
	v_add_f32_e32 v53, 1.0, v53
	v_rcp_f32_e32 v50, v50
	v_rcp_f32_e32 v51, v51
	v_rcp_f32_e32 v52, v52
	v_rcp_f32_e32 v53, v53
	v_lshlrev_b32_e32 v250, 16, v216
	v_and_b32_e32 v251, 0xffff0000, v216
	v_lshlrev_b32_e32 v252, 16, v217
	v_and_b32_e32 v253, 0xffff0000, v217
	v_pk_fma_f32 v[210:211], v[50:51], v[250:251], v[210:211]
	v_pk_fma_f32 v[212:213], v[52:53], v[252:253], v[212:213]
	global_store_dwordx4 v194, v[210:213], s[54:55] offset:576
	v_add_u32_e32 v194, 0x240000, v190
	v_pk_mul_f32 v[46:47], v[246:247], v[46:47] op_sel:[1,0] op_sel_hi:[1,1]
	v_pk_mul_f32 v[48:49], v[246:247], v[48:49] op_sel:[1,0] op_sel_hi:[1,1]
	v_pk_mul_f32 v[46:47], v[58:59], v[46:47]
	v_pk_mul_f32 v[48:49], v[60:61], v[48:49]
	v_mul_f32_e32 v46, v255, v46
	v_mul_f32_e32 v47, v255, v47
	v_mul_f32_e32 v48, v255, v48
	v_mul_f32_e32 v49, v255, v49
	v_exp_f32_e32 v46, v46
	v_exp_f32_e32 v47, v47
	v_exp_f32_e32 v48, v48
	v_exp_f32_e32 v49, v49
	v_add_f32_e32 v46, 1.0, v46
	v_add_f32_e32 v47, 1.0, v47
	v_add_f32_e32 v48, 1.0, v48
	v_add_f32_e32 v49, 1.0, v49
	v_rcp_f32_e32 v46, v46
	v_rcp_f32_e32 v47, v47
	v_rcp_f32_e32 v48, v48
	v_rcp_f32_e32 v49, v49
	s_waitcnt vmcnt(25)
	v_lshlrev_b32_e32 v250, 16, v126
	v_and_b32_e32 v251, 0xffff0000, v126
	v_lshlrev_b32_e32 v252, 16, v127
	v_and_b32_e32 v253, 0xffff0000, v127
	v_pk_fma_f32 v[142:143], v[46:47], v[250:251], v[142:143]
	v_pk_fma_f32 v[144:145], v[48:49], v[252:253], v[144:145]
	global_store_dwordx4 v194, v[142:145], s[54:55] offset:0
	v_pk_mul_f32 v[42:43], v[246:247], v[42:43] op_sel:[1,0] op_sel_hi:[1,1]
	v_pk_mul_f32 v[44:45], v[246:247], v[44:45] op_sel:[1,0] op_sel_hi:[1,1]
	v_pk_mul_f32 v[42:43], v[66:67], v[42:43]
	v_pk_mul_f32 v[44:45], v[68:69], v[44:45]
	v_mul_f32_e32 v42, v255, v42
	v_mul_f32_e32 v43, v255, v43
	v_mul_f32_e32 v44, v255, v44
	v_mul_f32_e32 v45, v255, v45
	v_exp_f32_e32 v42, v42
	v_exp_f32_e32 v43, v43
	v_exp_f32_e32 v44, v44
	v_exp_f32_e32 v45, v45
	v_add_f32_e32 v42, 1.0, v42
	v_add_f32_e32 v43, 1.0, v43
	v_add_f32_e32 v44, 1.0, v44
	v_add_f32_e32 v45, 1.0, v45
	v_rcp_f32_e32 v42, v42
	v_rcp_f32_e32 v43, v43
	v_rcp_f32_e32 v44, v44
	v_rcp_f32_e32 v45, v45
	v_lshlrev_b32_e32 v250, 16, v128
	v_and_b32_e32 v251, 0xffff0000, v128
	v_lshlrev_b32_e32 v252, 16, v129
	v_and_b32_e32 v253, 0xffff0000, v129
	v_pk_fma_f32 v[138:139], v[42:43], v[250:251], v[138:139]
	v_pk_fma_f32 v[140:141], v[44:45], v[252:253], v[140:141]
	global_store_dwordx4 v194, v[138:141], s[54:55] offset:64
	v_pk_mul_f32 v[38:39], v[246:247], v[38:39] op_sel:[1,0] op_sel_hi:[1,1]
	v_pk_mul_f32 v[40:41], v[246:247], v[40:41] op_sel:[1,0] op_sel_hi:[1,1]
	v_pk_mul_f32 v[38:39], v[74:75], v[38:39]
	v_pk_mul_f32 v[40:41], v[76:77], v[40:41]
	v_mul_f32_e32 v38, v255, v38
	v_mul_f32_e32 v39, v255, v39
	v_mul_f32_e32 v40, v255, v40
	v_mul_f32_e32 v41, v255, v41
	v_exp_f32_e32 v38, v38
	v_exp_f32_e32 v39, v39
	v_exp_f32_e32 v40, v40
	v_exp_f32_e32 v41, v41
	v_add_f32_e32 v38, 1.0, v38
	v_add_f32_e32 v39, 1.0, v39
	v_add_f32_e32 v40, 1.0, v40
	v_add_f32_e32 v41, 1.0, v41
	v_rcp_f32_e32 v38, v38
	v_rcp_f32_e32 v39, v39
	v_rcp_f32_e32 v40, v40
	v_rcp_f32_e32 v41, v41
	s_waitcnt vmcnt(26)
	v_lshlrev_b32_e32 v250, 16, v122
	v_and_b32_e32 v251, 0xffff0000, v122
	v_lshlrev_b32_e32 v252, 16, v123
	v_and_b32_e32 v253, 0xffff0000, v123
	v_pk_fma_f32 v[134:135], v[38:39], v[250:251], v[134:135]
	v_pk_fma_f32 v[136:137], v[40:41], v[252:253], v[136:137]
	global_store_dwordx4 v194, v[134:137], s[54:55] offset:512
	v_pk_mul_f32 v[34:35], v[246:247], v[34:35] op_sel:[1,0] op_sel_hi:[1,1]
	v_pk_mul_f32 v[36:37], v[246:247], v[36:37] op_sel:[1,0] op_sel_hi:[1,1]
	v_pk_mul_f32 v[34:35], v[78:79], v[34:35]
	v_pk_mul_f32 v[36:37], v[80:81], v[36:37]
	v_mul_f32_e32 v34, v255, v34
	v_mul_f32_e32 v35, v255, v35
	v_mul_f32_e32 v36, v255, v36
	v_mul_f32_e32 v37, v255, v37
	v_exp_f32_e32 v34, v34
	v_exp_f32_e32 v35, v35
	v_exp_f32_e32 v36, v36
	v_exp_f32_e32 v37, v37
	v_add_f32_e32 v34, 1.0, v34
	v_add_f32_e32 v35, 1.0, v35
	v_add_f32_e32 v36, 1.0, v36
	v_add_f32_e32 v37, 1.0, v37
	v_rcp_f32_e32 v34, v34
	v_rcp_f32_e32 v35, v35
	v_rcp_f32_e32 v36, v36
	v_rcp_f32_e32 v37, v37
	v_lshlrev_b32_e32 v250, 16, v124
	v_and_b32_e32 v251, 0xffff0000, v124
	v_lshlrev_b32_e32 v252, 16, v125
	v_and_b32_e32 v253, 0xffff0000, v125
	v_pk_fma_f32 v[130:131], v[34:35], v[250:251], v[130:131]
	v_pk_fma_f32 v[132:133], v[36:37], v[252:253], v[132:133]
	global_store_dwordx4 v194, v[130:133], s[54:55] offset:576
	v_add_u32_e32 v194, 0x280000, v190
	v_pk_mul_f32 v[30:31], v[248:249], v[30:31] op_sel:[0,0] op_sel_hi:[0,1]
	v_pk_mul_f32 v[32:33], v[248:249], v[32:33] op_sel:[0,0] op_sel_hi:[0,1]
	v_pk_mul_f32 v[30:31], v[58:59], v[30:31]
	v_pk_mul_f32 v[32:33], v[60:61], v[32:33]
	v_mul_f32_e32 v30, v255, v30
	v_mul_f32_e32 v31, v255, v31
	v_mul_f32_e32 v32, v255, v32
	v_mul_f32_e32 v33, v255, v33
	v_exp_f32_e32 v30, v30
	v_exp_f32_e32 v31, v31
	v_exp_f32_e32 v32, v32
	v_exp_f32_e32 v33, v33
	v_add_f32_e32 v30, 1.0, v30
	v_add_f32_e32 v31, 1.0, v31
	v_add_f32_e32 v32, 1.0, v32
	v_add_f32_e32 v33, 1.0, v33
	v_rcp_f32_e32 v30, v30
	v_rcp_f32_e32 v31, v31
	v_rcp_f32_e32 v32, v32
	v_rcp_f32_e32 v33, v33
	s_waitcnt vmcnt(19)
; __device__ __forceinline__ f32x4 sig4(const f32x4 v) { return (f32x4){sigmoidf_(v[0]), sigmoidf_(v[1]), sigmoidf_(v[2]), sigmoidf_(v[3])}; }
;     __device__ __forceinline__ void operator()(const typename AccT<I8>::type (&acc)[2][2][4][2], const Unit& u, int wr, int wc, int fr, int fq) const {
;     ...
;         for (int s = 0; s < 8; ++s) { const int ai = s >> 2, m = s & 3; const int r = row0 + ai * HALF + m * 16; const size_t off = (size_t)r * 4096 + col0;
;                 if (s + 1 < 8) load_row(nxt, (size_t)(row0 + ((s + 1) >> 2) * HALF + ((s + 1) & 3) * 16) * 4096 + col0);
;                 const float rs = rsv[s];
;                 float ss = 0.f, mx = 0.f;
; #pragma unroll
;                 for (int bj = 0; bj < 2; ++bj)
; #pragma unroll
;                     for (int n = 0; n < 2; ++n) { const size_t o = off + bj * HALF + n * 16; const f32x4 b = cur.b[bj][n]; f32x4 v;
;                         if constexpr (I8) v = __builtin_convertvector(acc[ai][bj][m][n], f32x4) * rs * sv[bj][n]; else v = acc[ai][bj][m][n];
;                         if (MODE == 1) { const u32x2 pw = cur.pw[bj][n]; const f32x4 pp = (f32x4){bf_lo(pw.x), bf_hi(pw.x), bf_lo(pw.y), bf_hi(pw.y)}; v = sig4(I8 ? v : v * rs) * pp; }
;                         const f32x4 x = b + v; *(f32x4*)(out + o) = x;
	v_lshlrev_b32_e32 v250, 16, v234
	v_and_b32_e32 v251, 0xffff0000, v234
	v_lshlrev_b32_e32 v252, 16, v235
	v_and_b32_e32 v253, 0xffff0000, v235
	v_pk_fma_f32 v[218:219], v[30:31], v[250:251], v[218:219]
	v_pk_fma_f32 v[220:221], v[32:33], v[252:253], v[220:221]
	global_store_dwordx4 v194, v[218:221], s[54:55] offset:0
	v_pk_mul_f32 v[26:27], v[248:249], v[26:27] op_sel:[0,0] op_sel_hi:[0,1]
	v_pk_mul_f32 v[28:29], v[248:249], v[28:29] op_sel:[0,0] op_sel_hi:[0,1]
	v_pk_mul_f32 v[26:27], v[66:67], v[26:27]
	v_pk_mul_f32 v[28:29], v[68:69], v[28:29]
	v_mul_f32_e32 v26, v255, v26
	v_mul_f32_e32 v27, v255, v27
	v_mul_f32_e32 v28, v255, v28
	v_mul_f32_e32 v29, v255, v29
	v_exp_f32_e32 v26, v26
	v_exp_f32_e32 v27, v27
	v_exp_f32_e32 v28, v28
	v_exp_f32_e32 v29, v29
	v_add_f32_e32 v26, 1.0, v26
	v_add_f32_e32 v27, 1.0, v27
	v_add_f32_e32 v28, 1.0, v28
	v_add_f32_e32 v29, 1.0, v29
	v_rcp_f32_e32 v26, v26
	v_rcp_f32_e32 v27, v27
	v_rcp_f32_e32 v28, v28
	v_rcp_f32_e32 v29, v29
	v_lshlrev_b32_e32 v250, 16, v236
	v_and_b32_e32 v251, 0xffff0000, v236
	v_lshlrev_b32_e32 v252, 16, v237
	v_and_b32_e32 v253, 0xffff0000, v237
	v_pk_fma_f32 v[222:223], v[26:27], v[250:251], v[222:223]
	v_pk_fma_f32 v[224:225], v[28:29], v[252:253], v[224:225]
	global_store_dwordx4 v194, v[222:225], s[54:55] offset:64
	v_pk_mul_f32 v[22:23], v[248:249], v[22:23] op_sel:[0,0] op_sel_hi:[0,1]
	v_pk_mul_f32 v[24:25], v[248:249], v[24:25] op_sel:[0,0] op_sel_hi:[0,1]
	v_pk_mul_f32 v[22:23], v[74:75], v[22:23]
	v_pk_mul_f32 v[24:25], v[76:77], v[24:25]
	v_mul_f32_e32 v22, v255, v22
	v_mul_f32_e32 v23, v255, v23
	v_mul_f32_e32 v24, v255, v24
	v_mul_f32_e32 v25, v255, v25
	v_exp_f32_e32 v22, v22
	v_exp_f32_e32 v23, v23
	v_exp_f32_e32 v24, v24
	v_exp_f32_e32 v25, v25
	v_add_f32_e32 v22, 1.0, v22
	v_add_f32_e32 v23, 1.0, v23
	v_add_f32_e32 v24, 1.0, v24
	v_add_f32_e32 v25, 1.0, v25
	v_rcp_f32_e32 v22, v22
	v_rcp_f32_e32 v23, v23
	v_rcp_f32_e32 v24, v24
	v_rcp_f32_e32 v25, v25
	s_waitcnt vmcnt(20)
	v_lshlrev_b32_e32 v250, 16, v238
	v_and_b32_e32 v251, 0xffff0000, v238
	v_lshlrev_b32_e32 v252, 16, v239
	v_and_b32_e32 v253, 0xffff0000, v239
	v_pk_fma_f32 v[226:227], v[22:23], v[250:251], v[226:227]
	v_pk_fma_f32 v[228:229], v[24:25], v[252:253], v[228:229]
	global_store_dwordx4 v194, v[226:229], s[54:55] offset:512
	v_pk_mul_f32 v[18:19], v[248:249], v[18:19] op_sel:[0,0] op_sel_hi:[0,1]
	v_pk_mul_f32 v[20:21], v[248:249], v[20:21] op_sel:[0,0] op_sel_hi:[0,1]
	v_pk_mul_f32 v[18:19], v[78:79], v[18:19]
	v_pk_mul_f32 v[20:21], v[80:81], v[20:21]
	v_mul_f32_e32 v18, v255, v18
	v_mul_f32_e32 v19, v255, v19
	v_mul_f32_e32 v20, v255, v20
	v_mul_f32_e32 v21, v255, v21
	v_exp_f32_e32 v18, v18
	v_exp_f32_e32 v19, v19
	v_exp_f32_e32 v20, v20
	v_exp_f32_e32 v21, v21
	v_add_f32_e32 v18, 1.0, v18
	v_add_f32_e32 v19, 1.0, v19
	v_add_f32_e32 v20, 1.0, v20
	v_add_f32_e32 v21, 1.0, v21
	v_rcp_f32_e32 v18, v18
	v_rcp_f32_e32 v19, v19
	v_rcp_f32_e32 v20, v20
	v_rcp_f32_e32 v21, v21
	v_lshlrev_b32_e32 v250, 16, v240
	v_and_b32_e32 v251, 0xffff0000, v240
	v_lshlrev_b32_e32 v252, 16, v241
	v_and_b32_e32 v253, 0xffff0000, v241
	v_pk_fma_f32 v[230:231], v[18:19], v[250:251], v[230:231]
	v_pk_fma_f32 v[232:233], v[20:21], v[252:253], v[232:233]
	global_store_dwordx4 v194, v[230:233], s[54:55] offset:576
	v_add_u32_e32 v194, 0x2c0000, v190
	v_pk_mul_f32 v[14:15], v[248:249], v[14:15] op_sel:[1,0] op_sel_hi:[1,1]
	v_pk_mul_f32 v[16:17], v[248:249], v[16:17] op_sel:[1,0] op_sel_hi:[1,1]
	v_pk_mul_f32 v[14:15], v[58:59], v[14:15]
	v_pk_mul_f32 v[16:17], v[60:61], v[16:17]
	v_mul_f32_e32 v14, v255, v14
	v_mul_f32_e32 v15, v255, v15
	v_mul_f32_e32 v16, v255, v16
	v_mul_f32_e32 v17, v255, v17
	v_exp_f32_e32 v14, v14
	v_exp_f32_e32 v15, v15
	v_exp_f32_e32 v16, v16
	v_exp_f32_e32 v17, v17
	v_add_f32_e32 v14, 1.0, v14
	v_add_f32_e32 v15, 1.0, v15
	v_add_f32_e32 v16, 1.0, v16
	v_add_f32_e32 v17, 1.0, v17
	v_rcp_f32_e32 v14, v14
	v_rcp_f32_e32 v15, v15
	v_rcp_f32_e32 v16, v16
	v_rcp_f32_e32 v17, v17
	s_waitcnt vmcnt(17)
; __device__ __forceinline__ f32x4 sig4(const f32x4 v) { return (f32x4){sigmoidf_(v[0]), sigmoidf_(v[1]), sigmoidf_(v[2]), sigmoidf_(v[3])}; }
;     __device__ __forceinline__ void operator()(const typename AccT<I8>::type (&acc)[2][2][4][2], const Unit& u, int wr, int wc, int fr, int fq) const {
;     ...
;         for (int s = 0; s < 8; ++s) { const int ai = s >> 2, m = s & 3; const int r = row0 + ai * HALF + m * 16; const size_t off = (size_t)r * 4096 + col0;
;                 if (s + 1 < 8) load_row(nxt, (size_t)(row0 + ((s + 1) >> 2) * HALF + ((s + 1) & 3) * 16) * 4096 + col0);
;                 const float rs = rsv[s];
;                 float ss = 0.f, mx = 0.f;
; #pragma unroll
;                 for (int bj = 0; bj < 2; ++bj)
; #pragma unroll
;                     for (int n = 0; n < 2; ++n) { const size_t o = off + bj * HALF + n * 16; const f32x4 b = cur.b[bj][n]; f32x4 v;
;                         if constexpr (I8) v = __builtin_convertvector(acc[ai][bj][m][n], f32x4) * rs * sv[bj][n]; else v = acc[ai][bj][m][n];
;                         if (MODE == 1) { const u32x2 pw = cur.pw[bj][n]; const f32x4 pp = (f32x4){bf_lo(pw.x), bf_hi(pw.x), bf_lo(pw.y), bf_hi(pw.y)}; v = sig4(I8 ? v : v * rs) * pp; }
;                         const f32x4 x = b + v; *(f32x4*)(out + o) = x;
	v_lshlrev_b32_e32 v250, 16, v118
	v_and_b32_e32 v251, 0xffff0000, v118
	v_lshlrev_b32_e32 v252, 16, v119
	v_and_b32_e32 v253, 0xffff0000, v119
	v_pk_fma_f32 v[110:111], v[14:15], v[250:251], v[110:111]
	v_pk_fma_f32 v[112:113], v[16:17], v[252:253], v[112:113]
	global_store_dwordx4 v194, v[110:113], s[54:55] offset:0
	v_pk_mul_f32 v[10:11], v[248:249], v[10:11] op_sel:[1,0] op_sel_hi:[1,1]
	v_pk_mul_f32 v[12:13], v[248:249], v[12:13] op_sel:[1,0] op_sel_hi:[1,1]
	v_pk_mul_f32 v[10:11], v[66:67], v[10:11]
	v_pk_mul_f32 v[12:13], v[68:69], v[12:13]
	v_mul_f32_e32 v10, v255, v10
	v_mul_f32_e32 v11, v255, v11
	v_mul_f32_e32 v12, v255, v12
	v_mul_f32_e32 v13, v255, v13
	v_exp_f32_e32 v10, v10
	v_exp_f32_e32 v11, v11
	v_exp_f32_e32 v12, v12
	v_exp_f32_e32 v13, v13
	v_add_f32_e32 v10, 1.0, v10
	v_add_f32_e32 v11, 1.0, v11
	v_add_f32_e32 v12, 1.0, v12
	v_add_f32_e32 v13, 1.0, v13
	v_rcp_f32_e32 v10, v10
	v_rcp_f32_e32 v11, v11
	v_rcp_f32_e32 v12, v12
	v_rcp_f32_e32 v13, v13
	v_lshlrev_b32_e32 v250, 16, v120
	v_and_b32_e32 v251, 0xffff0000, v120
	v_lshlrev_b32_e32 v252, 16, v121
	v_and_b32_e32 v253, 0xffff0000, v121
	v_pk_fma_f32 v[106:107], v[10:11], v[250:251], v[106:107]
	v_pk_fma_f32 v[108:109], v[12:13], v[252:253], v[108:109]
	global_store_dwordx4 v194, v[106:109], s[54:55] offset:64
	v_pk_mul_f32 v[6:7], v[248:249], v[6:7] op_sel:[1,0] op_sel_hi:[1,1]
	v_pk_mul_f32 v[8:9], v[248:249], v[8:9] op_sel:[1,0] op_sel_hi:[1,1]
	v_pk_mul_f32 v[6:7], v[74:75], v[6:7]
	v_pk_mul_f32 v[8:9], v[76:77], v[8:9]
	v_mul_f32_e32 v6, v255, v6
	v_mul_f32_e32 v7, v255, v7
	v_mul_f32_e32 v8, v255, v8
	v_mul_f32_e32 v9, v255, v9
	v_exp_f32_e32 v6, v6
	v_exp_f32_e32 v7, v7
	v_exp_f32_e32 v8, v8
	v_exp_f32_e32 v9, v9
	v_add_f32_e32 v6, 1.0, v6
	v_add_f32_e32 v7, 1.0, v7
	v_add_f32_e32 v8, 1.0, v8
	v_add_f32_e32 v9, 1.0, v9
	v_rcp_f32_e32 v6, v6
	v_rcp_f32_e32 v7, v7
	v_rcp_f32_e32 v8, v8
	v_rcp_f32_e32 v9, v9
	s_waitcnt vmcnt(18)
	v_lshlrev_b32_e32 v250, 16, v114
	v_and_b32_e32 v251, 0xffff0000, v114
	v_lshlrev_b32_e32 v252, 16, v115
	v_and_b32_e32 v253, 0xffff0000, v115
	v_pk_fma_f32 v[102:103], v[6:7], v[250:251], v[102:103]
	v_pk_fma_f32 v[104:105], v[8:9], v[252:253], v[104:105]
	global_store_dwordx4 v194, v[102:105], s[54:55] offset:512
	v_pk_mul_f32 v[2:3], v[248:249], v[2:3] op_sel:[1,0] op_sel_hi:[1,1]
	v_pk_mul_f32 v[4:5], v[248:249], v[4:5] op_sel:[1,0] op_sel_hi:[1,1]
	v_pk_mul_f32 v[2:3], v[78:79], v[2:3]
	v_pk_mul_f32 v[4:5], v[80:81], v[4:5]
	v_mul_f32_e32 v2, v255, v2
	v_mul_f32_e32 v3, v255, v3
	v_mul_f32_e32 v4, v255, v4
	v_mul_f32_e32 v5, v255, v5
	v_exp_f32_e32 v2, v2
	v_exp_f32_e32 v3, v3
	v_exp_f32_e32 v4, v4
	v_exp_f32_e32 v5, v5
	v_add_f32_e32 v2, 1.0, v2
	v_add_f32_e32 v3, 1.0, v3
	v_add_f32_e32 v4, 1.0, v4
	v_add_f32_e32 v5, 1.0, v5
	v_rcp_f32_e32 v2, v2
	v_rcp_f32_e32 v3, v3
	v_rcp_f32_e32 v4, v4
	v_rcp_f32_e32 v5, v5
	v_lshlrev_b32_e32 v250, 16, v116
	v_and_b32_e32 v251, 0xffff0000, v116
	v_lshlrev_b32_e32 v252, 16, v117
	v_and_b32_e32 v253, 0xffff0000, v117
	v_pk_fma_f32 v[98:99], v[2:3], v[250:251], v[98:99]
	v_pk_fma_f32 v[100:101], v[4:5], v[252:253], v[100:101]
	global_store_dwordx4 v194, v[98:101], s[54:55] offset:576
	v_readlane_b32 s48, v254, 8
	s_mov_b64 s[26:27], s[54:55]
	s_andn2_b64 vcc, exec, s[0:1]
	s_mov_b64 s[0:1], -1
	v_readlane_b32 s49, v254, 9
	v_readlane_b32 s50, v254, 10
	v_readlane_b32 s51, v254, 11
	v_readlane_b32 s52, v254, 12
	v_readlane_b32 s53, v254, 13
	s_cbranch_vccnz .LBB0_2314
	s_andn2_b64 vcc, exec, s[4:5]
	s_cbranch_vccnz .LBB0_2313
	s_barrier
	s_branch .LBB0_2313

; __global__ void __launch_bounds__(NWAVES * 64, 2) mk_fwd(Args args) {
	.amdhsa_kernel _Z6mk_fwd4Args
		.amdhsa_group_segment_fixed_size 0
		.amdhsa_private_segment_fixed_size 0
		.amdhsa_kernarg_size 496
		.amdhsa_user_sgpr_count 2
		.amdhsa_user_sgpr_dispatch_ptr 0
		.amdhsa_user_sgpr_queue_ptr 0
		.amdhsa_user_sgpr_kernarg_segment_ptr 1
		.amdhsa_user_sgpr_dispatch_id 0
		.amdhsa_user_sgpr_kernarg_preload_length 0
		.amdhsa_user_sgpr_kernarg_preload_offset 0
		.amdhsa_user_sgpr_private_segment_size 0
		.amdhsa_uses_dynamic_stack 0
		.amdhsa_enable_private_segment 0
		.amdhsa_system_sgpr_workgroup_id_x 1
		.amdhsa_system_sgpr_workgroup_id_y 0
		.amdhsa_system_sgpr_workgroup_id_z 0
		.amdhsa_system_sgpr_workgroup_info 0
		.amdhsa_system_vgpr_workitem_id 0
		.amdhsa_next_free_vgpr 256
		.amdhsa_next_free_sgpr 102
		.amdhsa_accum_offset 256
		.amdhsa_reserve_vcc 1
		.amdhsa_float_round_mode_32 0
		.amdhsa_float_round_mode_16_64 0
		.amdhsa_float_denorm_mode_32 3
		.amdhsa_float_denorm_mode_16_64 3
		.amdhsa_dx10_clamp 1
		.amdhsa_ieee_mode 1
		.amdhsa_fp16_overflow 0
		.amdhsa_tg_split 0
		.amdhsa_exception_fp_ieee_invalid_op 0
		.amdhsa_exception_fp_denorm_src 0
		.amdhsa_exception_fp_ieee_div_zero 0
		.amdhsa_exception_fp_ieee_overflow 0
		.amdhsa_exception_fp_ieee_underflow 0
		.amdhsa_exception_fp_ieee_inexact 0
		.amdhsa_exception_int_div_zero 0
	.end_amdhsa_kernel

; __global__ void __launch_bounds__(NWAVES * 64, 2) mk_fwd(Args args) {
amdhsa.kernels:
  - .agpr_count:     0
    .args:
      - .offset:         0
        .size:           240
        .value_kind:     by_value
      - .offset:         240
        .size:           4
        .value_kind:     hidden_block_count_x
      - .offset:         244
        .size:           4
        .value_kind:     hidden_block_count_y
      - .offset:         248
        .size:           4
        .value_kind:     hidden_block_count_z
      - .offset:         252
        .size:           2
        .value_kind:     hidden_group_size_x
      - .offset:         254
        .size:           2
        .value_kind:     hidden_group_size_y
      - .offset:         256
        .size:           2
        .value_kind:     hidden_group_size_z
      - .offset:         258
        .size:           2
        .value_kind:     hidden_remainder_x
      - .offset:         260
        .size:           2
        .value_kind:     hidden_remainder_y
      - .offset:         262
        .size:           2
        .value_kind:     hidden_remainder_z
      - .offset:         280
        .size:           8
        .value_kind:     hidden_global_offset_x
      - .offset:         288
        .size:           8
        .value_kind:     hidden_global_offset_y
      - .offset:         296
        .size:           8
        .value_kind:     hidden_global_offset_z
      - .offset:         304
        .size:           2
        .value_kind:     hidden_grid_dims
      - .offset:         360
        .size:           4
        .value_kind:     hidden_dynamic_lds_size
    .group_segment_fixed_size: 0
    .kernarg_segment_align: 8
    .kernarg_segment_size: 496
    .language:       OpenCL C
    .language_version:
      - 2
      - 0
    .max_flat_workgroup_size: 512
    .name:           _Z6mk_fwd4Args
    .private_segment_fixed_size: 0
    .sgpr_count:     108
    .sgpr_spill_count: 79
    .symbol:         _Z6mk_fwd4Args.kd
    .uniform_work_group_size: 1
    .uses_dynamic_stack: false
    .vgpr_count:     256
    .vgpr_spill_count: 0
    .wavefront_size: 64
